# prep S3: the four forward-substitution waves run at s_setprio 1 (their sibling waves fill the stalls)
# baseline (speedup 1.0000x reference)
.LBB0_191:
	s_andn2_saveexec_b64 s[20:21], s[20:21]
	s_cbranch_execz .LBB0_43
	s_movk_i32 s0, 0x7f
	v_cmp_lt_u32_e32 vcc, s0, v49
	s_movk_i32 s0, 0x80
	v_lshlrev_b32_e32 v0, 1, v49
	v_cmp_gt_u32_e64 s[0:1], s0, v49
	v_and_b32_e32 v47, 0x7f, v49
	v_and_b32_e32 v0, 0xffffff00, v0
	v_cndmask_b32_e64 v2, v232, v223, s[0:1]
	v_add_u32_e32 v0, 0x1d700, v0
	v_lshl_or_b32 v2, v47, 1, v2
	v_mov_b32_e32 v3, 0x19100
	v_cndmask_b32_e64 v55, v228, v229, s[0:1]
	v_add_u32_e32 v53, 0, v0
	v_add_u32_e32 v51, 0, v2
	v_add_u32_e32 v57, 0, v3
	s_setprio 1
	v_mov_b32_e32 v85, v1
	v_mov_b32_e32 v0, 0
	v_mov_b32_e32 v2, 0
	v_mov_b32_e32 v3, 0
	v_mov_b32_e32 v4, 0
	v_mov_b32_e32 v5, 0
	v_mov_b32_e32 v6, 0
	v_mov_b32_e32 v7, 0
	v_mov_b32_e32 v8, 0
	v_mov_b32_e32 v9, 0
	v_mov_b32_e32 v10, 0
	v_mov_b32_e32 v11, 0
	v_mov_b32_e32 v12, 0
	v_mov_b32_e32 v13, 0
	v_mov_b32_e32 v14, 0
	v_mov_b32_e32 v15, 0
	v_mov_b32_e32 v16, 0
	v_mov_b32_e32 v17, 0
	v_mov_b32_e32 v18, 0
	v_mov_b32_e32 v19, 0
	v_mov_b32_e32 v20, 0
	v_mov_b32_e32 v21, 0
	v_mov_b32_e32 v22, 0
	v_mov_b32_e32 v23, 0
	v_mov_b32_e32 v24, 0
	v_mov_b32_e32 v25, 0
	v_mov_b32_e32 v26, 0
	v_mov_b32_e32 v27, 0
	v_mov_b32_e32 v28, 0
	v_mov_b32_e32 v29, 0
	v_mov_b32_e32 v30, 0
	v_mov_b32_e32 v31, 0
	v_mov_b32_e32 v32, 0
	v_mov_b32_e32 v33, 0
	v_mov_b32_e32 v34, 0
	v_mov_b32_e32 v35, 0
	v_mov_b32_e32 v36, 0
	v_mov_b32_e32 v37, 0
	v_mov_b32_e32 v86, 0
	v_mov_b32_e32 v87, 0
	v_mov_b32_e32 v88, 0
	v_mov_b32_e32 v89, 0
	v_mov_b32_e32 v90, 0
	v_mov_b32_e32 v91, 0
	v_mov_b32_e32 v92, 0
	v_mov_b32_e32 v93, 0
	v_mov_b32_e32 v94, 0
	v_mov_b32_e32 v95, 0
	v_mov_b32_e32 v96, 0
	v_mov_b32_e32 v97, 0
	v_mov_b32_e32 v98, 0
	v_mov_b32_e32 v99, 0
	v_mov_b32_e32 v100, 0
	v_mov_b32_e32 v101, 0
	v_mov_b32_e32 v102, 0
	v_mov_b32_e32 v103, 0
	v_mov_b32_e32 v104, 0
	v_mov_b32_e32 v105, 0
	v_mov_b32_e32 v106, 0
	v_mov_b32_e32 v107, 0
	v_mov_b32_e32 v108, 0
	v_mov_b32_e32 v109, 0
	v_mov_b32_e32 v110, 0
	v_mov_b32_e32 v111, 0
	v_mov_b32_e32 v112, 0
	v_mov_b32_e32 v113, 0
	ds_read_u16 v221, v51
	ds_read_b32 v220, v53
	ds_read_b128 v[174:177], v57 offset:272
	v_mad_u32_u24 v61, v55, 1, v51
	ds_read_u16 v227, v61
	ds_read_b32 v226, v53 offset:4
	ds_read_b128 v[178:181], v57 offset:544
	v_mad_u32_u24 v61, v55, 2, v51
	ds_read_u16 v59, v61
	ds_read_b32 v204, v53 offset:8
	ds_read_b128 v[182:185], v57 offset:816
	s_waitcnt lgkmcnt(5)
	v_lshlrev_b32_e32 v221, 16, v221
	v_mul_f32_e32 v0, v220, v221
	v_mov_b32_e32 v2, v0
	v_mad_u32_u24 v61, v55, 3, v51
	ds_read_u16 v221, v61
	ds_read_b32 v220, v53 offset:12
	ds_read_b128 v[186:189], v57 offset:1088
	v_pk_fma_f32 v[250:251], v[174:175], v[2:3], 0 op_sel_hi:[1,1,0]
	v_pk_fma_f32 v[202:203], v[176:177], v[4:5], 0 op_sel_hi:[1,1,0]
	v_add_f32_e32 v250, v250, v251
	v_add_f32_e32 v202, v202, v203
	s_waitcnt lgkmcnt(5)
	v_lshlrev_b32_e32 v227, 16, v227
	v_add_f32_e32 v250, v250, v202
	v_fma_f32 v3, v226, v227, -v250
	v_mad_u32_u24 v61, v55, 4, v51
	ds_read_u16 v227, v61
	ds_read_b32 v226, v53 offset:16
	ds_read_b128 v[190:193], v57 offset:1360
	ds_read_b128 v[194:197], v57 offset:1376
	v_pk_fma_f32 v[246:247], v[178:179], v[2:3], 0 op_sel_hi:[1,1,0]
	v_pk_fma_f32 v[248:249], v[180:181], v[4:5], 0 op_sel_hi:[1,1,0]
	v_add_f32_e32 v246, v246, v247
	v_add_f32_e32 v248, v248, v249
	s_waitcnt lgkmcnt(5)
	v_lshlrev_b32_e32 v59, 16, v59
	v_add_f32_e32 v246, v246, v248
	v_fma_f32 v4, v204, v59, -v246
	v_mad_u32_u24 v61, v55, 5, v51
	ds_read_u16 v59, v61
	ds_read_b32 v204, v53 offset:20
	ds_read_b128 v[198:201], v57 offset:1632
	ds_read_b128 v[206:209], v57 offset:1648
	v_pk_fma_f32 v[250:251], v[182:183], v[2:3], 0 op_sel_hi:[1,1,0]
	v_pk_fma_f32 v[202:203], v[184:185], v[4:5], 0 op_sel_hi:[1,1,0]
	v_add_f32_e32 v250, v250, v251
	v_add_f32_e32 v202, v202, v203
	v_lshlrev_b32_e32 v221, 16, v221
	v_add_f32_e32 v250, v250, v202
	v_fma_f32 v5, v220, v221, -v250
	v_mad_u32_u24 v61, v55, 6, v51
	ds_read_u16 v221, v61
	ds_read_b32 v220, v53 offset:24
	ds_read_b128 v[210:213], v57 offset:1904
	ds_read_b128 v[214:217], v57 offset:1920
	s_waitcnt lgkmcnt(5)
	v_pk_fma_f32 v[246:247], v[186:187], v[2:3], 0 op_sel_hi:[1,1,0]
	v_pk_fma_f32 v[248:249], v[188:189], v[4:5], 0 op_sel_hi:[1,1,0]
	v_pk_fma_f32 v[250:251], v[190:191], v[2:3], 0 op_sel_hi:[1,1,0]
	v_pk_fma_f32 v[202:203], v[192:193], v[4:5], 0 op_sel_hi:[1,1,0]
	v_add_f32_e32 v246, v246, v247
	v_add_f32_e32 v248, v248, v249
	v_lshlrev_b32_e32 v227, 16, v227
	v_add_f32_e32 v246, v246, v248
	v_fma_f32 v6, v226, v227, -v246
	v_mad_u32_u24 v61, v55, 7, v51
	ds_read_u16 v227, v61
	ds_read_b32 v226, v53 offset:28
	ds_read_b128 v[238:241], v57 offset:2176
	ds_read_b128 v[242:245], v57 offset:2192
	v_pk_fma_f32 v[250:251], v[194:195], v[6:7], v[250:251]
	v_pk_fma_f32 v[202:203], v[196:197], v[8:9], v[202:203]
	v_pk_fma_f32 v[246:247], v[198:199], v[2:3], 0 op_sel_hi:[1,1,0]
	v_pk_fma_f32 v[248:249], v[200:201], v[4:5], 0 op_sel_hi:[1,1,0]
	v_add_f32_e32 v250, v250, v251
	v_add_f32_e32 v202, v202, v203
	v_lshlrev_b32_e32 v59, 16, v59
	v_add_f32_e32 v250, v250, v202
	v_fma_f32 v7, v204, v59, -v250
	v_mad_u32_u24 v61, v55, 8, v51
	ds_read_u16 v59, v61
	ds_read_b32 v204, v53 offset:32
	ds_read_b128 v[174:177], v57 offset:2448
	ds_read_b128 v[178:181], v57 offset:2464
	s_waitcnt lgkmcnt(5)
	v_pk_fma_f32 v[246:247], v[206:207], v[6:7], v[246:247]
	v_pk_fma_f32 v[248:249], v[208:209], v[8:9], v[248:249]
	ds_read_b128 v[182:185], v57 offset:2480
	v_pk_fma_f32 v[250:251], v[210:211], v[2:3], 0 op_sel_hi:[1,1,0]
	v_pk_fma_f32 v[202:203], v[212:213], v[4:5], 0 op_sel_hi:[1,1,0]
	v_add_f32_e32 v246, v246, v247
	v_add_f32_e32 v248, v248, v249
	v_lshlrev_b32_e32 v221, 16, v221
	v_add_f32_e32 v246, v246, v248
	v_fma_f32 v8, v220, v221, -v246
	v_mad_u32_u24 v61, v55, 9, v51
	ds_read_u16 v221, v61
	ds_read_b32 v220, v53 offset:36
	ds_read_b128 v[186:189], v57 offset:2720
	ds_read_b128 v[190:193], v57 offset:2736
	ds_read_b128 v[194:197], v57 offset:2752
	v_pk_fma_f32 v[250:251], v[214:215], v[6:7], v[250:251]
	v_pk_fma_f32 v[202:203], v[216:217], v[8:9], v[202:203]
	v_pk_fma_f32 v[246:247], v[238:239], v[2:3], 0 op_sel_hi:[1,1,0]
	v_pk_fma_f32 v[248:249], v[240:241], v[4:5], 0 op_sel_hi:[1,1,0]
	v_add_f32_e32 v250, v250, v251
	v_add_f32_e32 v202, v202, v203
	v_lshlrev_b32_e32 v227, 16, v227
	v_add_f32_e32 v250, v250, v202
	v_fma_f32 v9, v226, v227, -v250
	v_mad_u32_u24 v61, v55, 10, v51
	ds_read_u16 v227, v61
	ds_read_b32 v226, v53 offset:40
	s_waitcnt lgkmcnt(5)
	v_pk_fma_f32 v[246:247], v[242:243], v[6:7], v[246:247]
	v_pk_fma_f32 v[248:249], v[244:245], v[8:9], v[248:249]
	ds_read_b128 v[198:201], v57 offset:2992
	ds_read_b128 v[206:209], v57 offset:3008
	ds_read_b128 v[210:213], v57 offset:3024
	v_pk_fma_f32 v[250:251], v[174:175], v[2:3], 0 op_sel_hi:[1,1,0]
	v_pk_fma_f32 v[202:203], v[176:177], v[4:5], 0 op_sel_hi:[1,1,0]
	v_add_f32_e32 v246, v246, v247
	v_pk_fma_f32 v[250:251], v[178:179], v[6:7], v[250:251]
	v_pk_fma_f32 v[202:203], v[180:181], v[8:9], v[202:203]
	v_add_f32_e32 v248, v248, v249
	v_lshlrev_b32_e32 v59, 16, v59
	v_add_f32_e32 v246, v246, v248
	v_fma_f32 v10, v204, v59, -v246
	v_mad_u32_u24 v61, v55, 11, v51
	ds_read_u16 v59, v61
	ds_read_b32 v204, v53 offset:44
	ds_read_b128 v[214:217], v57 offset:3264
	ds_read_b128 v[238:241], v57 offset:3280
	ds_read_b128 v[242:245], v57 offset:3296
	v_pk_fma_f32 v[250:251], v[182:183], v[10:11], v[250:251]
	v_pk_fma_f32 v[202:203], v[184:185], v[12:13], v[202:203]
	s_waitcnt lgkmcnt(5)
	v_pk_fma_f32 v[246:247], v[186:187], v[2:3], 0 op_sel_hi:[1,1,0]
	v_pk_fma_f32 v[248:249], v[188:189], v[4:5], 0 op_sel_hi:[1,1,0]
	v_add_f32_e32 v250, v250, v251
	v_pk_fma_f32 v[246:247], v[190:191], v[6:7], v[246:247]
	v_pk_fma_f32 v[248:249], v[192:193], v[8:9], v[248:249]
	v_add_f32_e32 v202, v202, v203
	v_lshlrev_b32_e32 v221, 16, v221
	v_add_f32_e32 v250, v250, v202
	v_fma_f32 v11, v220, v221, -v250
	v_mad_u32_u24 v61, v55, 12, v51
	ds_read_u16 v221, v61
	ds_read_b32 v220, v53 offset:48
	ds_read_b128 v[174:177], v57 offset:3536
	ds_read_b128 v[178:181], v57 offset:3552
	ds_read_b128 v[182:185], v57 offset:3568
	ds_read_b128 v[186:189], v57 offset:3584
	v_pk_fma_f32 v[246:247], v[194:195], v[10:11], v[246:247]
	v_pk_fma_f32 v[248:249], v[196:197], v[12:13], v[248:249]
	v_pk_fma_f32 v[250:251], v[198:199], v[2:3], 0 op_sel_hi:[1,1,0]
	v_pk_fma_f32 v[202:203], v[200:201], v[4:5], 0 op_sel_hi:[1,1,0]
	v_add_f32_e32 v246, v246, v247
	v_pk_fma_f32 v[250:251], v[206:207], v[6:7], v[250:251]
	v_pk_fma_f32 v[202:203], v[208:209], v[8:9], v[202:203]
	v_add_f32_e32 v248, v248, v249
	v_lshlrev_b32_e32 v227, 16, v227
	v_add_f32_e32 v246, v246, v248
	v_fma_f32 v12, v226, v227, -v246
	v_mad_u32_u24 v61, v55, 13, v51
	ds_read_u16 v227, v61
	ds_read_b32 v226, v53 offset:52
	v_pk_fma_f32 v[250:251], v[210:211], v[10:11], v[250:251]
	v_pk_fma_f32 v[202:203], v[212:213], v[12:13], v[202:203]
	s_waitcnt lgkmcnt(5)
	v_pk_fma_f32 v[246:247], v[214:215], v[2:3], 0 op_sel_hi:[1,1,0]
	v_pk_fma_f32 v[248:249], v[216:217], v[4:5], 0 op_sel_hi:[1,1,0]
	ds_read_b128 v[190:193], v57 offset:3808
	ds_read_b128 v[194:197], v57 offset:3824
	ds_read_b128 v[198:201], v57 offset:3840
	ds_read_b128 v[206:209], v57 offset:3856
	v_add_f32_e32 v250, v250, v251
	v_pk_fma_f32 v[246:247], v[238:239], v[6:7], v[246:247]
	v_pk_fma_f32 v[248:249], v[240:241], v[8:9], v[248:249]
	v_add_f32_e32 v202, v202, v203
	v_lshlrev_b32_e32 v59, 16, v59
	v_add_f32_e32 v250, v250, v202
	v_fma_f32 v13, v204, v59, -v250
	v_mad_u32_u24 v61, v55, 14, v51
	ds_read_u16 v59, v61
	ds_read_b32 v204, v53 offset:56
	ds_read_b128 v[210:213], v57 offset:4080
	ds_read_b128 v[214:217], v57 offset:4096
	v_pk_fma_f32 v[246:247], v[242:243], v[10:11], v[246:247]
	v_pk_fma_f32 v[248:249], v[244:245], v[12:13], v[248:249]
	v_pk_fma_f32 v[250:251], v[174:175], v[2:3], 0 op_sel_hi:[1,1,0]
	v_pk_fma_f32 v[202:203], v[176:177], v[4:5], 0 op_sel_hi:[1,1,0]
	v_add_f32_e32 v246, v246, v247
	s_waitcnt lgkmcnt(5)
	v_pk_fma_f32 v[250:251], v[178:179], v[6:7], v[250:251]
	v_pk_fma_f32 v[202:203], v[180:181], v[8:9], v[202:203]
	ds_read_b128 v[238:241], v57 offset:4112
	ds_read_b128 v[242:245], v57 offset:4128
	v_add_f32_e32 v248, v248, v249
	v_pk_fma_f32 v[250:251], v[182:183], v[10:11], v[250:251]
	v_pk_fma_f32 v[202:203], v[184:185], v[12:13], v[202:203]
	v_lshlrev_b32_e32 v221, 16, v221
	v_add_f32_e32 v246, v246, v248
	v_fma_f32 v14, v220, v221, -v246
	v_mad_u32_u24 v61, v55, 15, v51
	ds_read_u16 v221, v61
	ds_read_b32 v220, v53 offset:60
	ds_read_b128 v[174:177], v57 offset:4352
	ds_read_b128 v[178:181], v57 offset:4368
	ds_read_b128 v[182:185], v57 offset:4384
	v_pk_fma_f32 v[250:251], v[186:187], v[14:15], v[250:251]
	v_pk_fma_f32 v[202:203], v[188:189], v[16:17], v[202:203]
	ds_read_b128 v[186:189], v57 offset:4400
	v_pk_fma_f32 v[246:247], v[190:191], v[2:3], 0 op_sel_hi:[1,1,0]
	v_pk_fma_f32 v[248:249], v[192:193], v[4:5], 0 op_sel_hi:[1,1,0]
	v_add_f32_e32 v250, v250, v251
	v_pk_fma_f32 v[246:247], v[194:195], v[6:7], v[246:247]
	v_pk_fma_f32 v[248:249], v[196:197], v[8:9], v[248:249]
	v_add_f32_e32 v202, v202, v203
	v_pk_fma_f32 v[246:247], v[198:199], v[10:11], v[246:247]
	v_pk_fma_f32 v[248:249], v[200:201], v[12:13], v[248:249]
	v_lshlrev_b32_e32 v227, 16, v227
	v_add_f32_e32 v250, v250, v202
	v_fma_f32 v15, v226, v227, -v250
	s_waitcnt lgkmcnt(5)
	v_pk_fma_f32 v[246:247], v[206:207], v[14:15], v[246:247]
	v_pk_fma_f32 v[248:249], v[208:209], v[16:17], v[248:249]
	v_mad_u32_u24 v61, v55, 16, v51
	ds_read_u16 v227, v61
	ds_read_b32 v226, v53 offset:64
	ds_read_b128 v[190:193], v57 offset:4624
	ds_read_b128 v[194:197], v57 offset:4640
	ds_read_b128 v[198:201], v57 offset:4656
	ds_read_b128 v[206:209], v57 offset:4672
	v_pk_fma_f32 v[250:251], v[210:211], v[2:3], 0 op_sel_hi:[1,1,0]
	v_pk_fma_f32 v[202:203], v[212:213], v[4:5], 0 op_sel_hi:[1,1,0]
	ds_read_b128 v[210:213], v57 offset:4688
	v_add_f32_e32 v246, v246, v247
	v_pk_fma_f32 v[250:251], v[214:215], v[6:7], v[250:251]
	v_pk_fma_f32 v[202:203], v[216:217], v[8:9], v[202:203]
	v_add_f32_e32 v248, v248, v249
	v_pk_fma_f32 v[250:251], v[238:239], v[10:11], v[250:251]
	v_pk_fma_f32 v[202:203], v[240:241], v[12:13], v[202:203]
	v_lshlrev_b32_e32 v59, 16, v59
	v_add_f32_e32 v246, v246, v248
	v_fma_f32 v16, v204, v59, -v246
	v_pk_fma_f32 v[250:251], v[242:243], v[14:15], v[250:251]
	v_pk_fma_f32 v[202:203], v[244:245], v[16:17], v[202:203]
	s_waitcnt lgkmcnt(5)
	v_pk_fma_f32 v[246:247], v[174:175], v[2:3], 0 op_sel_hi:[1,1,0]
	v_pk_fma_f32 v[248:249], v[176:177], v[4:5], 0 op_sel_hi:[1,1,0]
	v_mad_u32_u24 v61, v55, 17, v51
	ds_read_u16 v59, v61
	ds_read_b32 v204, v53 offset:68
	ds_read_b128 v[214:217], v57 offset:4896
	ds_read_b128 v[238:241], v57 offset:4912
	ds_read_b128 v[242:245], v57 offset:4928
	ds_read_b128 v[174:177], v57 offset:4944
	v_add_f32_e32 v250, v250, v251
	v_pk_fma_f32 v[246:247], v[178:179], v[6:7], v[246:247]
	v_pk_fma_f32 v[248:249], v[180:181], v[8:9], v[248:249]
	ds_read_b128 v[178:181], v57 offset:4960
	v_add_f32_e32 v202, v202, v203
	v_pk_fma_f32 v[246:247], v[182:183], v[10:11], v[246:247]
	v_pk_fma_f32 v[248:249], v[184:185], v[12:13], v[248:249]
	v_lshlrev_b32_e32 v221, 16, v221
	v_add_f32_e32 v250, v250, v202
	v_fma_f32 v17, v220, v221, -v250
	v_pk_fma_f32 v[246:247], v[186:187], v[14:15], v[246:247]
	v_pk_fma_f32 v[248:249], v[188:189], v[16:17], v[248:249]
	s_waitcnt lgkmcnt(5)
	v_pk_fma_f32 v[250:251], v[190:191], v[2:3], 0 op_sel_hi:[1,1,0]
	v_pk_fma_f32 v[202:203], v[192:193], v[4:5], 0 op_sel_hi:[1,1,0]
	v_mad_u32_u24 v61, v55, 18, v51
	ds_read_u16 v221, v61
	ds_read_b32 v220, v53 offset:72
	ds_read_b128 v[182:185], v57 offset:5168
	ds_read_b128 v[186:189], v57 offset:5184
	ds_read_b128 v[190:193], v57 offset:5200
	v_add_f32_e32 v246, v246, v247
	v_pk_fma_f32 v[250:251], v[194:195], v[6:7], v[250:251]
	v_pk_fma_f32 v[202:203], v[196:197], v[8:9], v[202:203]
	ds_read_b128 v[194:197], v57 offset:5216
	v_add_f32_e32 v248, v248, v249
	v_pk_fma_f32 v[250:251], v[198:199], v[10:11], v[250:251]
	v_pk_fma_f32 v[202:203], v[200:201], v[12:13], v[202:203]
	ds_read_b128 v[198:201], v57 offset:5232
	v_lshlrev_b32_e32 v227, 16, v227
	v_pk_fma_f32 v[250:251], v[206:207], v[14:15], v[250:251]
	v_pk_fma_f32 v[202:203], v[208:209], v[16:17], v[202:203]
	v_add_f32_e32 v246, v246, v248
	v_fma_f32 v18, v226, v227, -v246
	v_pk_fma_f32 v[250:251], v[210:211], v[18:19], v[250:251]
	v_pk_fma_f32 v[202:203], v[212:213], v[20:21], v[202:203]
	s_waitcnt lgkmcnt(5)
	v_pk_fma_f32 v[246:247], v[214:215], v[2:3], 0 op_sel_hi:[1,1,0]
	v_pk_fma_f32 v[248:249], v[216:217], v[4:5], 0 op_sel_hi:[1,1,0]
	v_mad_u32_u24 v61, v55, 19, v51
	ds_read_u16 v227, v61
	ds_read_b32 v226, v53 offset:76
	ds_read_b128 v[206:209], v57 offset:5440
	ds_read_b128 v[210:213], v57 offset:5456
	ds_read_b128 v[214:217], v57 offset:5472
	v_add_f32_e32 v250, v250, v251
	v_pk_fma_f32 v[246:247], v[238:239], v[6:7], v[246:247]
	v_pk_fma_f32 v[248:249], v[240:241], v[8:9], v[248:249]
	ds_read_b128 v[238:241], v57 offset:5488
	v_add_f32_e32 v202, v202, v203
	v_pk_fma_f32 v[246:247], v[242:243], v[10:11], v[246:247]
	v_pk_fma_f32 v[248:249], v[244:245], v[12:13], v[248:249]
	ds_read_b128 v[242:245], v57 offset:5504
	v_lshlrev_b32_e32 v59, 16, v59
	v_pk_fma_f32 v[246:247], v[174:175], v[14:15], v[246:247]
	v_pk_fma_f32 v[248:249], v[176:177], v[16:17], v[248:249]
	v_add_f32_e32 v250, v250, v202
	v_fma_f32 v19, v204, v59, -v250
	v_pk_fma_f32 v[246:247], v[178:179], v[18:19], v[246:247]
	v_pk_fma_f32 v[248:249], v[180:181], v[20:21], v[248:249]
	s_waitcnt lgkmcnt(5)
	v_pk_fma_f32 v[250:251], v[182:183], v[2:3], 0 op_sel_hi:[1,1,0]
	v_pk_fma_f32 v[202:203], v[184:185], v[4:5], 0 op_sel_hi:[1,1,0]
	v_mad_u32_u24 v61, v55, 20, v51
	ds_read_u16 v59, v61
	ds_read_b32 v204, v53 offset:80
	ds_read_b128 v[174:177], v57 offset:5712
	ds_read_b128 v[178:181], v57 offset:5728
	ds_read_b128 v[182:185], v57 offset:5744
	v_add_f32_e32 v246, v246, v247
	v_pk_fma_f32 v[250:251], v[186:187], v[6:7], v[250:251]
	v_pk_fma_f32 v[202:203], v[188:189], v[8:9], v[202:203]
	ds_read_b128 v[186:189], v57 offset:5760
	v_add_f32_e32 v248, v248, v249
	v_pk_fma_f32 v[250:251], v[190:191], v[10:11], v[250:251]
	v_pk_fma_f32 v[202:203], v[192:193], v[12:13], v[202:203]
	ds_read_b128 v[190:193], v57 offset:5776
	v_lshlrev_b32_e32 v221, 16, v221
	v_pk_fma_f32 v[250:251], v[194:195], v[14:15], v[250:251]
	v_pk_fma_f32 v[202:203], v[196:197], v[16:17], v[202:203]
	ds_read_b128 v[194:197], v57 offset:5792
	v_add_f32_e32 v246, v246, v248
	v_fma_f32 v20, v220, v221, -v246
	v_pk_fma_f32 v[250:251], v[198:199], v[18:19], v[250:251]
	v_pk_fma_f32 v[202:203], v[200:201], v[20:21], v[202:203]
	s_waitcnt lgkmcnt(5)
	v_pk_fma_f32 v[246:247], v[206:207], v[2:3], 0 op_sel_hi:[1,1,0]
	v_pk_fma_f32 v[248:249], v[208:209], v[4:5], 0 op_sel_hi:[1,1,0]
	v_mad_u32_u24 v61, v55, 21, v51
	ds_read_u16 v221, v61
	ds_read_b32 v220, v53 offset:84
	ds_read_b128 v[198:201], v57 offset:5984
	ds_read_b128 v[206:209], v57 offset:6000
	v_add_f32_e32 v250, v250, v251
	v_pk_fma_f32 v[246:247], v[210:211], v[6:7], v[246:247]
	v_pk_fma_f32 v[248:249], v[212:213], v[8:9], v[248:249]
	ds_read_b128 v[210:213], v57 offset:6016
	v_add_f32_e32 v202, v202, v203
	v_pk_fma_f32 v[246:247], v[214:215], v[10:11], v[246:247]
	v_pk_fma_f32 v[248:249], v[216:217], v[12:13], v[248:249]
	ds_read_b128 v[214:217], v57 offset:6032
	v_lshlrev_b32_e32 v227, 16, v227
	v_pk_fma_f32 v[246:247], v[238:239], v[14:15], v[246:247]
	v_pk_fma_f32 v[248:249], v[240:241], v[16:17], v[248:249]
	ds_read_b128 v[238:241], v57 offset:6048
	v_add_f32_e32 v250, v250, v202
	v_fma_f32 v21, v226, v227, -v250
	v_pk_fma_f32 v[246:247], v[242:243], v[18:19], v[246:247]
	v_pk_fma_f32 v[248:249], v[244:245], v[20:21], v[248:249]
	ds_read_b128 v[242:245], v57 offset:6064
	v_pk_fma_f32 v[250:251], v[174:175], v[2:3], 0 op_sel_hi:[1,1,0]
	v_pk_fma_f32 v[202:203], v[176:177], v[4:5], 0 op_sel_hi:[1,1,0]
	v_add_f32_e32 v246, v246, v247
	s_waitcnt lgkmcnt(5)
	v_pk_fma_f32 v[250:251], v[178:179], v[6:7], v[250:251]
	v_pk_fma_f32 v[202:203], v[180:181], v[8:9], v[202:203]
	v_mad_u32_u24 v61, v55, 22, v51
	ds_read_u16 v227, v61
	ds_read_b32 v226, v53 offset:88
	ds_read_b128 v[174:177], v57 offset:6256
	ds_read_b128 v[178:181], v57 offset:6272
	v_add_f32_e32 v248, v248, v249
	v_pk_fma_f32 v[250:251], v[182:183], v[10:11], v[250:251]
	v_pk_fma_f32 v[202:203], v[184:185], v[12:13], v[202:203]
	ds_read_b128 v[182:185], v57 offset:6288
	v_lshlrev_b32_e32 v59, 16, v59
	v_pk_fma_f32 v[250:251], v[186:187], v[14:15], v[250:251]
	v_pk_fma_f32 v[202:203], v[188:189], v[16:17], v[202:203]
	ds_read_b128 v[186:189], v57 offset:6304
	v_add_f32_e32 v246, v246, v248
	v_pk_fma_f32 v[250:251], v[190:191], v[18:19], v[250:251]
	v_pk_fma_f32 v[202:203], v[192:193], v[20:21], v[202:203]
	ds_read_b128 v[190:193], v57 offset:6320
	v_fma_f32 v22, v204, v59, -v246
	v_pk_fma_f32 v[250:251], v[194:195], v[22:23], v[250:251]
	v_pk_fma_f32 v[202:203], v[196:197], v[24:25], v[202:203]
	ds_read_b128 v[194:197], v57 offset:6336
	v_pk_fma_f32 v[246:247], v[198:199], v[2:3], 0 op_sel_hi:[1,1,0]
	v_pk_fma_f32 v[248:249], v[200:201], v[4:5], 0 op_sel_hi:[1,1,0]
	v_add_f32_e32 v250, v250, v251
	s_waitcnt lgkmcnt(5)
	v_pk_fma_f32 v[246:247], v[206:207], v[6:7], v[246:247]
	v_pk_fma_f32 v[248:249], v[208:209], v[8:9], v[248:249]
	v_mad_u32_u24 v61, v55, 23, v51
	ds_read_u16 v59, v61
	ds_read_b32 v204, v53 offset:92
	ds_read_b128 v[198:201], v57 offset:6528
	ds_read_b128 v[206:209], v57 offset:6544
	v_add_f32_e32 v202, v202, v203
	v_pk_fma_f32 v[246:247], v[210:211], v[10:11], v[246:247]
	v_pk_fma_f32 v[248:249], v[212:213], v[12:13], v[248:249]
	ds_read_b128 v[210:213], v57 offset:6560
	v_lshlrev_b32_e32 v221, 16, v221
	v_pk_fma_f32 v[246:247], v[214:215], v[14:15], v[246:247]
	v_pk_fma_f32 v[248:249], v[216:217], v[16:17], v[248:249]
	ds_read_b128 v[214:217], v57 offset:6576
	v_add_f32_e32 v250, v250, v202
	v_pk_fma_f32 v[246:247], v[238:239], v[18:19], v[246:247]
	v_pk_fma_f32 v[248:249], v[240:241], v[20:21], v[248:249]
	ds_read_b128 v[238:241], v57 offset:6592
	v_fma_f32 v23, v220, v221, -v250
	v_pk_fma_f32 v[246:247], v[242:243], v[22:23], v[246:247]
	v_pk_fma_f32 v[248:249], v[244:245], v[24:25], v[248:249]
	ds_read_b128 v[242:245], v57 offset:6608
	v_pk_fma_f32 v[250:251], v[174:175], v[2:3], 0 op_sel_hi:[1,1,0]
	v_pk_fma_f32 v[202:203], v[176:177], v[4:5], 0 op_sel_hi:[1,1,0]
	v_add_f32_e32 v246, v246, v247
	s_waitcnt lgkmcnt(5)
	v_pk_fma_f32 v[250:251], v[178:179], v[6:7], v[250:251]
	v_pk_fma_f32 v[202:203], v[180:181], v[8:9], v[202:203]
	v_mad_u32_u24 v61, v55, 24, v51
	ds_read_u16 v221, v61
	ds_read_b32 v220, v53 offset:96
	ds_read_b128 v[174:177], v57 offset:6800
	ds_read_b128 v[178:181], v57 offset:6816
	v_add_f32_e32 v248, v248, v249
	v_pk_fma_f32 v[250:251], v[182:183], v[10:11], v[250:251]
	v_pk_fma_f32 v[202:203], v[184:185], v[12:13], v[202:203]
	ds_read_b128 v[182:185], v57 offset:6832
	v_lshlrev_b32_e32 v227, 16, v227
	v_pk_fma_f32 v[250:251], v[186:187], v[14:15], v[250:251]
	v_pk_fma_f32 v[202:203], v[188:189], v[16:17], v[202:203]
	ds_read_b128 v[186:189], v57 offset:6848
	v_add_f32_e32 v246, v246, v248
	v_pk_fma_f32 v[250:251], v[190:191], v[18:19], v[250:251]
	v_pk_fma_f32 v[202:203], v[192:193], v[20:21], v[202:203]
	ds_read_b128 v[190:193], v57 offset:6864
	v_fma_f32 v24, v226, v227, -v246
	v_pk_fma_f32 v[250:251], v[194:195], v[22:23], v[250:251]
	v_pk_fma_f32 v[202:203], v[196:197], v[24:25], v[202:203]
	ds_read_b128 v[194:197], v57 offset:6880
	v_pk_fma_f32 v[246:247], v[198:199], v[2:3], 0 op_sel_hi:[1,1,0]
	v_pk_fma_f32 v[248:249], v[200:201], v[4:5], 0 op_sel_hi:[1,1,0]
	v_add_f32_e32 v250, v250, v251
	s_waitcnt lgkmcnt(5)
	v_pk_fma_f32 v[246:247], v[206:207], v[6:7], v[246:247]
	v_pk_fma_f32 v[248:249], v[208:209], v[8:9], v[248:249]
	ds_read_b128 v[198:201], v57 offset:6896
	v_mad_u32_u24 v61, v55, 25, v51
	ds_read_u16 v227, v61
	ds_read_b32 v226, v53 offset:100
	ds_read_b128 v[206:209], v57 offset:7072
	v_add_f32_e32 v202, v202, v203
	v_pk_fma_f32 v[246:247], v[210:211], v[10:11], v[246:247]
	v_pk_fma_f32 v[248:249], v[212:213], v[12:13], v[248:249]
	ds_read_b128 v[210:213], v57 offset:7088
	v_lshlrev_b32_e32 v59, 16, v59
	v_pk_fma_f32 v[246:247], v[214:215], v[14:15], v[246:247]
	v_pk_fma_f32 v[248:249], v[216:217], v[16:17], v[248:249]
	ds_read_b128 v[214:217], v57 offset:7104
	v_add_f32_e32 v250, v250, v202
	v_pk_fma_f32 v[246:247], v[238:239], v[18:19], v[246:247]
	v_pk_fma_f32 v[248:249], v[240:241], v[20:21], v[248:249]
	ds_read_b128 v[238:241], v57 offset:7120
	v_fma_f32 v25, v204, v59, -v250
	v_pk_fma_f32 v[246:247], v[242:243], v[22:23], v[246:247]
	v_pk_fma_f32 v[248:249], v[244:245], v[24:25], v[248:249]
	ds_read_b128 v[242:245], v57 offset:7136
	v_pk_fma_f32 v[250:251], v[174:175], v[2:3], 0 op_sel_hi:[1,1,0]
	v_pk_fma_f32 v[202:203], v[176:177], v[4:5], 0 op_sel_hi:[1,1,0]
	v_add_f32_e32 v246, v246, v247
	s_waitcnt lgkmcnt(5)
	v_pk_fma_f32 v[250:251], v[178:179], v[6:7], v[250:251]
	v_pk_fma_f32 v[202:203], v[180:181], v[8:9], v[202:203]
	ds_read_b128 v[174:177], v57 offset:7152
	ds_read_b128 v[178:181], v57 offset:7168
	v_mad_u32_u24 v61, v55, 26, v51
	ds_read_u16 v59, v61
	ds_read_b32 v204, v53 offset:104
	v_add_f32_e32 v248, v248, v249
	v_pk_fma_f32 v[250:251], v[182:183], v[10:11], v[250:251]
	v_pk_fma_f32 v[202:203], v[184:185], v[12:13], v[202:203]
	ds_read_b128 v[182:185], v57 offset:7344
	v_lshlrev_b32_e32 v221, 16, v221
	v_pk_fma_f32 v[250:251], v[186:187], v[14:15], v[250:251]
	v_pk_fma_f32 v[202:203], v[188:189], v[16:17], v[202:203]
	ds_read_b128 v[186:189], v57 offset:7360
	v_add_f32_e32 v246, v246, v248
	v_pk_fma_f32 v[250:251], v[190:191], v[18:19], v[250:251]
	v_pk_fma_f32 v[202:203], v[192:193], v[20:21], v[202:203]
	ds_read_b128 v[190:193], v57 offset:7376
	v_fma_f32 v26, v220, v221, -v246
	v_pk_fma_f32 v[250:251], v[194:195], v[22:23], v[250:251]
	v_pk_fma_f32 v[202:203], v[196:197], v[24:25], v[202:203]
	ds_read_b128 v[194:197], v57 offset:7392
	v_pk_fma_f32 v[250:251], v[198:199], v[26:27], v[250:251]
	v_pk_fma_f32 v[202:203], v[200:201], v[28:29], v[202:203]
	s_waitcnt lgkmcnt(5)
	v_pk_fma_f32 v[246:247], v[206:207], v[2:3], 0 op_sel_hi:[1,1,0]
	v_pk_fma_f32 v[248:249], v[208:209], v[4:5], 0 op_sel_hi:[1,1,0]
	ds_read_b128 v[198:201], v57 offset:7408
	ds_read_b128 v[206:209], v57 offset:7424
	v_add_f32_e32 v250, v250, v251
	v_pk_fma_f32 v[246:247], v[210:211], v[6:7], v[246:247]
	v_pk_fma_f32 v[248:249], v[212:213], v[8:9], v[248:249]
	ds_read_b128 v[210:213], v57 offset:7440
	v_mad_u32_u24 v61, v55, 27, v51
	ds_read_u16 v221, v61
	ds_read_b32 v220, v53 offset:108
	v_add_f32_e32 v202, v202, v203
	v_pk_fma_f32 v[246:247], v[214:215], v[10:11], v[246:247]
	v_pk_fma_f32 v[248:249], v[216:217], v[12:13], v[248:249]
	ds_read_b128 v[214:217], v57 offset:7616
	v_lshlrev_b32_e32 v227, 16, v227
	v_pk_fma_f32 v[246:247], v[238:239], v[14:15], v[246:247]
	v_pk_fma_f32 v[248:249], v[240:241], v[16:17], v[248:249]
	ds_read_b128 v[238:241], v57 offset:7632
	v_add_f32_e32 v250, v250, v202
	v_pk_fma_f32 v[246:247], v[242:243], v[18:19], v[246:247]
	v_pk_fma_f32 v[248:249], v[244:245], v[20:21], v[248:249]
	ds_read_b128 v[242:245], v57 offset:7648
	v_fma_f32 v27, v226, v227, -v250
	v_pk_fma_f32 v[246:247], v[174:175], v[22:23], v[246:247]
	v_pk_fma_f32 v[248:249], v[176:177], v[24:25], v[248:249]
	v_pk_fma_f32 v[246:247], v[178:179], v[26:27], v[246:247]
	v_pk_fma_f32 v[248:249], v[180:181], v[28:29], v[248:249]
	s_waitcnt lgkmcnt(5)
	v_pk_fma_f32 v[250:251], v[182:183], v[2:3], 0 op_sel_hi:[1,1,0]
	v_pk_fma_f32 v[202:203], v[184:185], v[4:5], 0 op_sel_hi:[1,1,0]
	ds_read_b128 v[174:177], v57 offset:7664
	ds_read_b128 v[178:181], v57 offset:7680
	ds_read_b128 v[182:185], v57 offset:7696
	v_add_f32_e32 v246, v246, v247
	v_pk_fma_f32 v[250:251], v[186:187], v[6:7], v[250:251]
	v_pk_fma_f32 v[202:203], v[188:189], v[8:9], v[202:203]
	ds_read_b128 v[186:189], v57 offset:7712
	v_mad_u32_u24 v61, v55, 28, v51
	ds_read_u16 v227, v61
	ds_read_b32 v226, v53 offset:112
	v_add_f32_e32 v248, v248, v249
	v_pk_fma_f32 v[250:251], v[190:191], v[10:11], v[250:251]
	v_pk_fma_f32 v[202:203], v[192:193], v[12:13], v[202:203]
	ds_read_b128 v[190:193], v57 offset:7888
	v_lshlrev_b32_e32 v59, 16, v59
	v_pk_fma_f32 v[250:251], v[194:195], v[14:15], v[250:251]
	v_pk_fma_f32 v[202:203], v[196:197], v[16:17], v[202:203]
	ds_read_b128 v[194:197], v57 offset:7904
	v_add_f32_e32 v246, v246, v248
	v_pk_fma_f32 v[250:251], v[198:199], v[18:19], v[250:251]
	v_pk_fma_f32 v[202:203], v[200:201], v[20:21], v[202:203]
	v_fma_f32 v28, v204, v59, -v246
	v_pk_fma_f32 v[250:251], v[206:207], v[22:23], v[250:251]
	v_pk_fma_f32 v[202:203], v[208:209], v[24:25], v[202:203]
	v_pk_fma_f32 v[250:251], v[210:211], v[26:27], v[250:251]
	v_pk_fma_f32 v[202:203], v[212:213], v[28:29], v[202:203]
	s_waitcnt lgkmcnt(5)
	v_pk_fma_f32 v[246:247], v[214:215], v[2:3], 0 op_sel_hi:[1,1,0]
	v_pk_fma_f32 v[248:249], v[216:217], v[4:5], 0 op_sel_hi:[1,1,0]
	ds_read_b128 v[198:201], v57 offset:7920
	ds_read_b128 v[206:209], v57 offset:7936
	ds_read_b128 v[210:213], v57 offset:7952
	ds_read_b128 v[214:217], v57 offset:7968
	v_add_f32_e32 v250, v250, v251
	v_pk_fma_f32 v[246:247], v[238:239], v[6:7], v[246:247]
	v_pk_fma_f32 v[248:249], v[240:241], v[8:9], v[248:249]
	ds_read_b128 v[238:241], v57 offset:7984
	v_add_f32_e32 v202, v202, v203
	v_pk_fma_f32 v[246:247], v[242:243], v[10:11], v[246:247]
	v_pk_fma_f32 v[248:249], v[244:245], v[12:13], v[248:249]
	ds_read_b128 v[242:245], v57 offset:8000
	v_mad_u32_u24 v61, v55, 29, v51
	ds_read_u16 v59, v61
	ds_read_b32 v204, v53 offset:116
	v_lshlrev_b32_e32 v221, 16, v221
	v_pk_fma_f32 v[246:247], v[174:175], v[14:15], v[246:247]
	v_pk_fma_f32 v[248:249], v[176:177], v[16:17], v[248:249]
	v_add_f32_e32 v250, v250, v202
	v_pk_fma_f32 v[246:247], v[178:179], v[18:19], v[246:247]
	v_pk_fma_f32 v[248:249], v[180:181], v[20:21], v[248:249]
	v_fma_f32 v29, v220, v221, -v250
	v_pk_fma_f32 v[246:247], v[182:183], v[22:23], v[246:247]
	v_pk_fma_f32 v[248:249], v[184:185], v[24:25], v[248:249]
	s_waitcnt lgkmcnt(5)
	v_pk_fma_f32 v[246:247], v[186:187], v[26:27], v[246:247]
	v_pk_fma_f32 v[248:249], v[188:189], v[28:29], v[248:249]
	ds_read_b128 v[174:177], v57 offset:8160
	ds_read_b128 v[178:181], v57 offset:8176
	ds_read_b128 v[182:185], v57 offset:8192
	ds_read_b128 v[186:189], v57 offset:8208
	v_pk_fma_f32 v[250:251], v[190:191], v[2:3], 0 op_sel_hi:[1,1,0]
	v_pk_fma_f32 v[202:203], v[192:193], v[4:5], 0 op_sel_hi:[1,1,0]
	ds_read_b128 v[190:193], v57 offset:8224
	v_add_f32_e32 v246, v246, v247
	v_pk_fma_f32 v[250:251], v[194:195], v[6:7], v[250:251]
	v_pk_fma_f32 v[202:203], v[196:197], v[8:9], v[202:203]
	ds_read_b128 v[194:197], v57 offset:8240
	v_add_f32_e32 v248, v248, v249
	v_pk_fma_f32 v[250:251], v[198:199], v[10:11], v[250:251]
	v_pk_fma_f32 v[202:203], v[200:201], v[12:13], v[202:203]
	ds_read_b128 v[198:201], v57 offset:8256
	v_lshlrev_b32_e32 v227, 16, v227
	v_pk_fma_f32 v[250:251], v[206:207], v[14:15], v[250:251]
	v_pk_fma_f32 v[202:203], v[208:209], v[16:17], v[202:203]
	ds_read_b128 v[206:209], v57 offset:8272
	v_add_f32_e32 v246, v246, v248
	v_pk_fma_f32 v[250:251], v[210:211], v[18:19], v[250:251]
	v_pk_fma_f32 v[202:203], v[212:213], v[20:21], v[202:203]
	v_fma_f32 v30, v226, v227, -v246
	s_waitcnt lgkmcnt(5)
	v_pk_fma_f32 v[250:251], v[214:215], v[22:23], v[250:251]
	v_pk_fma_f32 v[202:203], v[216:217], v[24:25], v[202:203]
	v_mad_u32_u24 v61, v55, 30, v51
	ds_read_u16 v221, v61
	ds_read_b32 v220, v53 offset:120
	ds_read_b128 v[210:213], v57 offset:8432
	ds_read_b128 v[214:217], v57 offset:8448
	v_pk_fma_f32 v[250:251], v[238:239], v[26:27], v[250:251]
	v_pk_fma_f32 v[202:203], v[240:241], v[28:29], v[202:203]
	ds_read_b128 v[238:241], v57 offset:8464
	v_pk_fma_f32 v[250:251], v[242:243], v[30:31], v[250:251]
	v_pk_fma_f32 v[202:203], v[244:245], v[32:33], v[202:203]
	ds_read_b128 v[242:245], v57 offset:8480
	v_pk_fma_f32 v[246:247], v[174:175], v[2:3], 0 op_sel_hi:[1,1,0]
	v_pk_fma_f32 v[248:249], v[176:177], v[4:5], 0 op_sel_hi:[1,1,0]
	ds_read_b128 v[174:177], v57 offset:8496
	v_add_f32_e32 v250, v250, v251
	v_pk_fma_f32 v[246:247], v[178:179], v[6:7], v[246:247]
	v_pk_fma_f32 v[248:249], v[180:181], v[8:9], v[248:249]
	ds_read_b128 v[178:181], v57 offset:8512
	v_add_f32_e32 v202, v202, v203
	v_pk_fma_f32 v[246:247], v[182:183], v[10:11], v[246:247]
	v_pk_fma_f32 v[248:249], v[184:185], v[12:13], v[248:249]
	v_lshlrev_b32_e32 v59, 16, v59
	s_waitcnt lgkmcnt(5)
	v_pk_fma_f32 v[246:247], v[186:187], v[14:15], v[246:247]
	v_pk_fma_f32 v[248:249], v[188:189], v[16:17], v[248:249]
	ds_read_b128 v[182:185], v57 offset:8528
	ds_read_b128 v[186:189], v57 offset:8544
	v_mad_u32_u24 v61, v55, 31, v51
	ds_read_u16 v227, v61
	ds_read_b32 v226, v53 offset:124
	v_add_f32_e32 v250, v250, v202
	v_pk_fma_f32 v[246:247], v[190:191], v[18:19], v[246:247]
	v_pk_fma_f32 v[248:249], v[192:193], v[20:21], v[248:249]
	v_fma_f32 v31, v204, v59, -v250
	v_mad_u32_u24 v61, v55, 32, v51
	ds_read_u16 v59, v61
	ds_read_b32 v204, v53 offset:128
	v_pk_fma_f32 v[246:247], v[194:195], v[22:23], v[246:247]
	v_pk_fma_f32 v[248:249], v[196:197], v[24:25], v[248:249]
	v_pk_fma_f32 v[246:247], v[198:199], v[26:27], v[246:247]
	v_pk_fma_f32 v[248:249], v[200:201], v[28:29], v[248:249]
	ds_read_b128 v[198:201], v57 offset:9104
	v_pk_fma_f32 v[246:247], v[206:207], v[30:31], v[246:247]
	v_pk_fma_f32 v[248:249], v[208:209], v[32:33], v[248:249]
	v_pk_fma_f32 v[250:251], v[210:211], v[2:3], 0 op_sel_hi:[1,1,0]
	v_pk_fma_f32 v[202:203], v[212:213], v[4:5], 0 op_sel_hi:[1,1,0]
	v_add_f32_e32 v246, v246, v247
	s_waitcnt lgkmcnt(5)
	v_pk_fma_f32 v[250:251], v[214:215], v[6:7], v[250:251]
	v_pk_fma_f32 v[202:203], v[216:217], v[8:9], v[202:203]
	v_add_f32_e32 v248, v248, v249
	v_pk_fma_f32 v[250:251], v[238:239], v[10:11], v[250:251]
	v_pk_fma_f32 v[202:203], v[240:241], v[12:13], v[202:203]
	v_lshlrev_b32_e32 v221, 16, v221
	v_pk_fma_f32 v[250:251], v[242:243], v[14:15], v[250:251]
	v_pk_fma_f32 v[202:203], v[244:245], v[16:17], v[202:203]
	v_add_f32_e32 v246, v246, v248
	v_pk_fma_f32 v[250:251], v[174:175], v[18:19], v[250:251]
	v_pk_fma_f32 v[202:203], v[176:177], v[20:21], v[202:203]
	v_fma_f32 v32, v220, v221, -v246
	v_mad_u32_u24 v61, v55, 33, v51
	ds_read_u16 v221, v61
	ds_read_b32 v220, v53 offset:132
	ds_read_b128 v[206:209], v57 offset:9376
	v_pk_fma_f32 v[250:251], v[178:179], v[22:23], v[250:251]
	v_pk_fma_f32 v[202:203], v[180:181], v[24:25], v[202:203]
	v_pk_fma_f32 v[250:251], v[182:183], v[26:27], v[250:251]
	v_pk_fma_f32 v[202:203], v[184:185], v[28:29], v[202:203]
	v_pk_fma_f32 v[250:251], v[186:187], v[30:31], v[250:251]
	v_pk_fma_f32 v[202:203], v[188:189], v[32:33], v[202:203]
	v_add_f32_e32 v250, v250, v251
	v_add_f32_e32 v202, v202, v203
	s_waitcnt lgkmcnt(5)
	v_lshlrev_b32_e32 v227, 16, v227
	v_add_f32_e32 v250, v250, v202
	v_fma_f32 v33, v226, v227, -v250
	v_mad_u32_u24 v61, v55, 34, v51
	ds_read_u16 v227, v61
	ds_read_b32 v226, v53 offset:136
	ds_read_b128 v[210:213], v57 offset:9648
	s_waitcnt lgkmcnt(6)
	v_and_b32_e32 v203, 31, v222
	v_mul_u32_u24_e32 v203, 0x110, v203
	v_lshrrev_b32_e32 v202, 5, v222
	v_lshl_add_u32 v202, v202, 2, v203
	v_add_u32_e32 v202, v202, v57
	ds_read_b32 v190, v202 offset:8704
	ds_read_b32 v191, v202 offset:8712
	ds_read_b32 v192, v202 offset:8720
	ds_read_b32 v193, v202 offset:8728
	ds_read_b32 v194, v202 offset:8736
	ds_read_b32 v195, v202 offset:8744
	ds_read_b32 v196, v202 offset:8752
	ds_read_b32 v197, v202 offset:8760
	v_mov_b32_e32 v246, v0
	v_mov_b32_e32 v247, v3
	s_nop 1
	v_permlane32_swap_b32_e32 v246, v247
	s_waitcnt lgkmcnt(7)
	s_nop 1
	v_mfma_f32_32x32x2_f32 v[174:189], v190, v246, 0
	v_mfma_f32_32x32x2_f32 v[98:113], v190, v247, 0
	ds_read_b32 v190, v202 offset:8768
	v_mov_b32_e32 v248, v4
	v_mov_b32_e32 v249, v5
	s_nop 1
	v_permlane32_swap_b32_e32 v248, v249
	s_waitcnt lgkmcnt(7)
	s_nop 1
	v_mfma_f32_32x32x2_f32 v[174:189], v191, v248, v[174:189]
	v_mfma_f32_32x32x2_f32 v[98:113], v191, v249, v[98:113]
	ds_read_b32 v191, v202 offset:8776
	v_mov_b32_e32 v250, v6
	v_mov_b32_e32 v251, v7
	s_nop 1
	v_permlane32_swap_b32_e32 v250, v251
	s_waitcnt lgkmcnt(7)
	s_nop 1
	v_mfma_f32_32x32x2_f32 v[174:189], v192, v250, v[174:189]
	v_mfma_f32_32x32x2_f32 v[98:113], v192, v251, v[98:113]
	ds_read_b32 v192, v202 offset:8784
	v_mov_b32_e32 v246, v8
	v_mov_b32_e32 v247, v9
	s_nop 1
	v_permlane32_swap_b32_e32 v246, v247
	s_waitcnt lgkmcnt(7)
	s_nop 1
	v_mfma_f32_32x32x2_f32 v[174:189], v193, v246, v[174:189]
	v_mfma_f32_32x32x2_f32 v[98:113], v193, v247, v[98:113]
	ds_read_b32 v193, v202 offset:8792
	v_mov_b32_e32 v248, v10
	v_mov_b32_e32 v249, v11
	s_nop 1
	v_permlane32_swap_b32_e32 v248, v249
	s_waitcnt lgkmcnt(7)
	s_nop 1
	v_mfma_f32_32x32x2_f32 v[174:189], v194, v248, v[174:189]
	v_mfma_f32_32x32x2_f32 v[98:113], v194, v249, v[98:113]
	ds_read_b32 v194, v202 offset:8800
	v_mov_b32_e32 v250, v12
	v_mov_b32_e32 v251, v13
	s_nop 1
	v_permlane32_swap_b32_e32 v250, v251
	s_waitcnt lgkmcnt(7)
	s_nop 1
	v_mfma_f32_32x32x2_f32 v[174:189], v195, v250, v[174:189]
	v_mfma_f32_32x32x2_f32 v[98:113], v195, v251, v[98:113]
	ds_read_b32 v195, v202 offset:8808
	v_mov_b32_e32 v246, v14
	v_mov_b32_e32 v247, v15
	s_nop 1
	v_permlane32_swap_b32_e32 v246, v247
	s_waitcnt lgkmcnt(7)
	s_nop 1
	v_mfma_f32_32x32x2_f32 v[174:189], v196, v246, v[174:189]
	v_mfma_f32_32x32x2_f32 v[98:113], v196, v247, v[98:113]
	ds_read_b32 v196, v202 offset:8816
	v_mov_b32_e32 v248, v16
	v_mov_b32_e32 v249, v17
	s_nop 1
	v_permlane32_swap_b32_e32 v248, v249
	s_waitcnt lgkmcnt(7)
	s_nop 1
	v_mfma_f32_32x32x2_f32 v[174:189], v197, v248, v[174:189]
	v_mfma_f32_32x32x2_f32 v[98:113], v197, v249, v[98:113]
	ds_read_b32 v197, v202 offset:8824
	v_mov_b32_e32 v250, v18
	v_mov_b32_e32 v251, v19
	s_nop 1
	v_permlane32_swap_b32_e32 v250, v251
	s_waitcnt lgkmcnt(7)
	s_nop 1
	v_mfma_f32_32x32x2_f32 v[174:189], v190, v250, v[174:189]
	v_mfma_f32_32x32x2_f32 v[98:113], v190, v251, v[98:113]
	v_mov_b32_e32 v246, v20
	v_mov_b32_e32 v247, v21
	s_nop 1
	v_permlane32_swap_b32_e32 v246, v247
	s_waitcnt lgkmcnt(6)
	s_nop 1
	v_mfma_f32_32x32x2_f32 v[174:189], v191, v246, v[174:189]
	v_mfma_f32_32x32x2_f32 v[98:113], v191, v247, v[98:113]
	v_mov_b32_e32 v248, v22
	v_mov_b32_e32 v249, v23
	s_nop 1
	v_permlane32_swap_b32_e32 v248, v249
	s_waitcnt lgkmcnt(5)
	s_nop 1
	v_mfma_f32_32x32x2_f32 v[174:189], v192, v248, v[174:189]
	v_mfma_f32_32x32x2_f32 v[98:113], v192, v249, v[98:113]
	v_mov_b32_e32 v250, v24
	v_mov_b32_e32 v251, v25
	s_nop 1
	v_permlane32_swap_b32_e32 v250, v251
	s_waitcnt lgkmcnt(4)
	s_nop 1
	v_mfma_f32_32x32x2_f32 v[174:189], v193, v250, v[174:189]
	v_mfma_f32_32x32x2_f32 v[98:113], v193, v251, v[98:113]
	v_mov_b32_e32 v246, v26
	v_mov_b32_e32 v247, v27
	s_nop 1
	v_permlane32_swap_b32_e32 v246, v247
	s_waitcnt lgkmcnt(3)
	s_nop 1
	v_mfma_f32_32x32x2_f32 v[174:189], v194, v246, v[174:189]
	v_mfma_f32_32x32x2_f32 v[98:113], v194, v247, v[98:113]
	v_mov_b32_e32 v248, v28
	v_mov_b32_e32 v249, v29
	s_nop 1
	v_permlane32_swap_b32_e32 v248, v249
	s_waitcnt lgkmcnt(2)
	s_nop 1
	v_mfma_f32_32x32x2_f32 v[174:189], v195, v248, v[174:189]
	v_mfma_f32_32x32x2_f32 v[98:113], v195, v249, v[98:113]
	v_mov_b32_e32 v250, v30
	v_mov_b32_e32 v251, v31
	s_nop 1
	v_permlane32_swap_b32_e32 v250, v251
	s_waitcnt lgkmcnt(1)
	s_nop 1
	v_mfma_f32_32x32x2_f32 v[174:189], v196, v250, v[174:189]
	v_mfma_f32_32x32x2_f32 v[98:113], v196, v251, v[98:113]
	v_mov_b32_e32 v246, v32
	v_mov_b32_e32 v247, v33
	s_nop 1
	v_permlane32_swap_b32_e32 v246, v247
	s_waitcnt lgkmcnt(0)
	s_nop 1
	v_mfma_f32_32x32x2_f32 v[174:189], v197, v246, v[174:189]
	v_mfma_f32_32x32x2_f32 v[98:113], v197, v247, v[98:113]
	s_nop 15
	s_nop 7
	v_permlane32_swap_b32_e32 v174, v98
	v_permlane32_swap_b32_e32 v175, v99
	v_permlane32_swap_b32_e32 v176, v100
	v_permlane32_swap_b32_e32 v177, v101
	v_permlane32_swap_b32_e32 v178, v102
	v_permlane32_swap_b32_e32 v179, v103
	v_permlane32_swap_b32_e32 v180, v104
	v_permlane32_swap_b32_e32 v181, v105
	v_permlane32_swap_b32_e32 v182, v106
	v_permlane32_swap_b32_e32 v183, v107
	v_permlane32_swap_b32_e32 v184, v108
	v_permlane32_swap_b32_e32 v185, v109
	v_permlane32_swap_b32_e32 v186, v110
	v_permlane32_swap_b32_e32 v187, v111
	v_permlane32_swap_b32_e32 v188, v112
	v_permlane32_swap_b32_e32 v189, v113
	v_lshlrev_b32_e32 v59, 16, v59
	v_fma_f32 v34, v204, v59, -v174
	v_mad_u32_u24 v61, v55, 35, v51
	ds_read_u16 v59, v61
	ds_read_b32 v204, v53 offset:140
	ds_read_b128 v[190:193], v57 offset:9920
	v_pk_fma_f32 v[250:251], v[198:199], v[34:35], 0 op_sel_hi:[1,1,0]
	v_pk_fma_f32 v[202:203], v[200:201], v[36:37], 0 op_sel_hi:[1,1,0]
	v_add_f32_e32 v250, v250, v251
	v_add_f32_e32 v202, v202, v203
	v_lshlrev_b32_e32 v221, 16, v221
	v_add_f32_e32 v250, v250, v202
	v_add_f32_e32 v250, v250, v175
	v_fma_f32 v35, v220, v221, -v250
	v_mad_u32_u24 v61, v55, 36, v51
	ds_read_u16 v221, v61
	ds_read_b32 v220, v53 offset:144
	ds_read_b128 v[194:197], v57 offset:10192
	ds_read_b128 v[214:217], v57 offset:10208
	v_pk_fma_f32 v[246:247], v[206:207], v[34:35], 0 op_sel_hi:[1,1,0]
	v_pk_fma_f32 v[248:249], v[208:209], v[36:37], 0 op_sel_hi:[1,1,0]
	v_add_f32_e32 v246, v246, v247
	v_add_f32_e32 v248, v248, v249
	v_lshlrev_b32_e32 v227, 16, v227
	v_add_f32_e32 v246, v246, v248
	v_add_f32_e32 v246, v246, v176
	v_fma_f32 v36, v226, v227, -v246
	v_mad_u32_u24 v61, v55, 37, v51
	ds_read_u16 v227, v61
	ds_read_b32 v226, v53 offset:148
	ds_read_b128 v[238:241], v57 offset:10464
	ds_read_b128 v[242:245], v57 offset:10480
	v_pk_fma_f32 v[250:251], v[210:211], v[34:35], 0 op_sel_hi:[1,1,0]
	v_pk_fma_f32 v[202:203], v[212:213], v[36:37], 0 op_sel_hi:[1,1,0]
	v_add_f32_e32 v250, v250, v251
	v_add_f32_e32 v202, v202, v203
	s_waitcnt lgkmcnt(5)
	v_lshlrev_b32_e32 v59, 16, v59
	v_add_f32_e32 v250, v250, v202
	v_add_f32_e32 v250, v250, v177
	v_fma_f32 v37, v204, v59, -v250
	v_mad_u32_u24 v61, v55, 38, v51
	ds_read_u16 v59, v61
	ds_read_b32 v204, v53 offset:152
	ds_read_b128 v[198:201], v57 offset:10736
	ds_read_b128 v[206:209], v57 offset:10752
	v_pk_fma_f32 v[246:247], v[190:191], v[34:35], 0 op_sel_hi:[1,1,0]
	v_pk_fma_f32 v[248:249], v[192:193], v[36:37], 0 op_sel_hi:[1,1,0]
	v_pk_fma_f32 v[250:251], v[194:195], v[34:35], 0 op_sel_hi:[1,1,0]
	v_pk_fma_f32 v[202:203], v[196:197], v[36:37], 0 op_sel_hi:[1,1,0]
	v_add_f32_e32 v246, v246, v247
	v_add_f32_e32 v248, v248, v249
	v_lshlrev_b32_e32 v221, 16, v221
	v_add_f32_e32 v246, v246, v248
	v_add_f32_e32 v246, v246, v98
	v_fma_f32 v86, v220, v221, -v246
	v_mad_u32_u24 v61, v55, 39, v51
	ds_read_u16 v221, v61
	ds_read_b32 v220, v53 offset:156
	ds_read_b128 v[210:213], v57 offset:11008
	ds_read_b128 v[190:193], v57 offset:11024
	s_waitcnt lgkmcnt(5)
	v_pk_fma_f32 v[250:251], v[214:215], v[86:87], v[250:251]
	v_pk_fma_f32 v[202:203], v[216:217], v[88:89], v[202:203]
	v_pk_fma_f32 v[246:247], v[238:239], v[34:35], 0 op_sel_hi:[1,1,0]
	v_pk_fma_f32 v[248:249], v[240:241], v[36:37], 0 op_sel_hi:[1,1,0]
	v_add_f32_e32 v250, v250, v251
	v_add_f32_e32 v202, v202, v203
	v_lshlrev_b32_e32 v227, 16, v227
	v_add_f32_e32 v250, v250, v202
	v_add_f32_e32 v250, v250, v99
	v_fma_f32 v87, v226, v227, -v250
	v_mad_u32_u24 v61, v55, 40, v51
	ds_read_u16 v227, v61
	ds_read_b32 v226, v53 offset:160
	ds_read_b128 v[194:197], v57 offset:11280
	ds_read_b128 v[214:217], v57 offset:11296
	ds_read_b128 v[238:241], v57 offset:11312
	v_pk_fma_f32 v[246:247], v[242:243], v[86:87], v[246:247]
	v_pk_fma_f32 v[248:249], v[244:245], v[88:89], v[248:249]
	v_pk_fma_f32 v[250:251], v[198:199], v[34:35], 0 op_sel_hi:[1,1,0]
	v_pk_fma_f32 v[202:203], v[200:201], v[36:37], 0 op_sel_hi:[1,1,0]
	v_add_f32_e32 v246, v246, v247
	v_add_f32_e32 v248, v248, v249
	v_lshlrev_b32_e32 v59, 16, v59
	v_add_f32_e32 v246, v246, v248
	v_add_f32_e32 v246, v246, v100
	v_fma_f32 v88, v204, v59, -v246
	v_mad_u32_u24 v61, v55, 41, v51
	ds_read_u16 v59, v61
	ds_read_b32 v204, v53 offset:164
	ds_read_b128 v[242:245], v57 offset:11552
	s_waitcnt lgkmcnt(5)
	v_pk_fma_f32 v[250:251], v[206:207], v[86:87], v[250:251]
	v_pk_fma_f32 v[202:203], v[208:209], v[88:89], v[202:203]
	ds_read_b128 v[198:201], v57 offset:11568
	ds_read_b128 v[206:209], v57 offset:11584
	v_pk_fma_f32 v[246:247], v[210:211], v[34:35], 0 op_sel_hi:[1,1,0]
	v_pk_fma_f32 v[248:249], v[212:213], v[36:37], 0 op_sel_hi:[1,1,0]
	v_add_f32_e32 v250, v250, v251
	v_add_f32_e32 v202, v202, v203
	v_lshlrev_b32_e32 v221, 16, v221
	v_add_f32_e32 v250, v250, v202
	v_add_f32_e32 v250, v250, v101
	v_fma_f32 v89, v220, v221, -v250
	v_mad_u32_u24 v61, v55, 42, v51
	ds_read_u16 v221, v61
	ds_read_b32 v220, v53 offset:168
	ds_read_b128 v[210:213], v57 offset:11824
	v_pk_fma_f32 v[246:247], v[190:191], v[86:87], v[246:247]
	v_pk_fma_f32 v[248:249], v[192:193], v[88:89], v[248:249]
	ds_read_b128 v[190:193], v57 offset:11840
	v_pk_fma_f32 v[250:251], v[194:195], v[34:35], 0 op_sel_hi:[1,1,0]
	v_pk_fma_f32 v[202:203], v[196:197], v[36:37], 0 op_sel_hi:[1,1,0]
	ds_read_b128 v[194:197], v57 offset:11856
	v_add_f32_e32 v246, v246, v247
	s_waitcnt lgkmcnt(5)
	v_pk_fma_f32 v[250:251], v[214:215], v[86:87], v[250:251]
	v_pk_fma_f32 v[202:203], v[216:217], v[88:89], v[202:203]
	v_add_f32_e32 v248, v248, v249
	v_lshlrev_b32_e32 v227, 16, v227
	v_add_f32_e32 v246, v246, v248
	v_add_f32_e32 v246, v246, v178
	v_fma_f32 v90, v226, v227, -v246
	v_mad_u32_u24 v61, v55, 43, v51
	ds_read_u16 v227, v61
	ds_read_b32 v226, v53 offset:172
	ds_read_b128 v[214:217], v57 offset:12096
	v_pk_fma_f32 v[250:251], v[238:239], v[90:91], v[250:251]
	v_pk_fma_f32 v[202:203], v[240:241], v[92:93], v[202:203]
	ds_read_b128 v[238:241], v57 offset:12112
	v_pk_fma_f32 v[246:247], v[242:243], v[34:35], 0 op_sel_hi:[1,1,0]
	v_pk_fma_f32 v[248:249], v[244:245], v[36:37], 0 op_sel_hi:[1,1,0]
	ds_read_b128 v[242:245], v57 offset:12128
	v_add_f32_e32 v250, v250, v251
	v_pk_fma_f32 v[246:247], v[198:199], v[86:87], v[246:247]
	v_pk_fma_f32 v[248:249], v[200:201], v[88:89], v[248:249]
	v_add_f32_e32 v202, v202, v203
	v_lshlrev_b32_e32 v59, 16, v59
	v_add_f32_e32 v250, v250, v202
	v_add_f32_e32 v250, v250, v179
	v_fma_f32 v91, v204, v59, -v250
	v_mad_u32_u24 v61, v55, 44, v51
	ds_read_u16 v59, v61
	ds_read_b32 v204, v53 offset:176
	ds_read_b128 v[198:201], v57 offset:12368
	v_pk_fma_f32 v[246:247], v[206:207], v[90:91], v[246:247]
	v_pk_fma_f32 v[248:249], v[208:209], v[92:93], v[248:249]
	s_waitcnt lgkmcnt(5)
	v_pk_fma_f32 v[250:251], v[210:211], v[34:35], 0 op_sel_hi:[1,1,0]
	v_pk_fma_f32 v[202:203], v[212:213], v[36:37], 0 op_sel_hi:[1,1,0]
	ds_read_b128 v[206:209], v57 offset:12384
	ds_read_b128 v[210:213], v57 offset:12400
	v_add_f32_e32 v246, v246, v247
	v_pk_fma_f32 v[250:251], v[190:191], v[86:87], v[250:251]
	v_pk_fma_f32 v[202:203], v[192:193], v[88:89], v[202:203]
	ds_read_b128 v[190:193], v57 offset:12416
	v_add_f32_e32 v248, v248, v249
	v_lshlrev_b32_e32 v221, 16, v221
	v_add_f32_e32 v246, v246, v248
	v_add_f32_e32 v246, v246, v180
	v_fma_f32 v92, v220, v221, -v246
	v_mad_u32_u24 v61, v55, 45, v51
	ds_read_u16 v221, v61
	ds_read_b32 v220, v53 offset:180
	v_pk_fma_f32 v[250:251], v[194:195], v[90:91], v[250:251]
	v_pk_fma_f32 v[202:203], v[196:197], v[92:93], v[202:203]
	ds_read_b128 v[194:197], v57 offset:12640
	v_pk_fma_f32 v[246:247], v[214:215], v[34:35], 0 op_sel_hi:[1,1,0]
	v_pk_fma_f32 v[248:249], v[216:217], v[36:37], 0 op_sel_hi:[1,1,0]
	ds_read_b128 v[214:217], v57 offset:12656
	v_add_f32_e32 v250, v250, v251
	s_waitcnt lgkmcnt(5)
	v_pk_fma_f32 v[246:247], v[238:239], v[86:87], v[246:247]
	v_pk_fma_f32 v[248:249], v[240:241], v[88:89], v[248:249]
	ds_read_b128 v[238:241], v57 offset:12672
	v_add_f32_e32 v202, v202, v203
	v_lshlrev_b32_e32 v227, 16, v227
	v_add_f32_e32 v250, v250, v202
	v_add_f32_e32 v250, v250, v181
	v_fma_f32 v93, v226, v227, -v250
	v_pk_fma_f32 v[246:247], v[242:243], v[90:91], v[246:247]
	v_pk_fma_f32 v[248:249], v[244:245], v[92:93], v[248:249]
	ds_read_b128 v[242:245], v57 offset:12688
	v_mad_u32_u24 v61, v55, 46, v51
	ds_read_u16 v227, v61
	ds_read_b32 v226, v53 offset:184
	v_pk_fma_f32 v[250:251], v[198:199], v[34:35], 0 op_sel_hi:[1,1,0]
	v_pk_fma_f32 v[202:203], v[200:201], v[36:37], 0 op_sel_hi:[1,1,0]
	ds_read_b128 v[198:201], v57 offset:12912
	v_add_f32_e32 v246, v246, v247
	v_pk_fma_f32 v[250:251], v[206:207], v[86:87], v[250:251]
	v_pk_fma_f32 v[202:203], v[208:209], v[88:89], v[202:203]
	ds_read_b128 v[206:209], v57 offset:12928
	v_add_f32_e32 v248, v248, v249
	v_pk_fma_f32 v[250:251], v[210:211], v[90:91], v[250:251]
	v_pk_fma_f32 v[202:203], v[212:213], v[92:93], v[202:203]
	ds_read_b128 v[210:213], v57 offset:12944
	v_lshlrev_b32_e32 v59, 16, v59
	v_add_f32_e32 v246, v246, v248
	v_add_f32_e32 v246, v246, v102
	v_fma_f32 v94, v204, v59, -v246
	s_waitcnt lgkmcnt(5)
	v_pk_fma_f32 v[250:251], v[190:191], v[94:95], v[250:251]
	v_pk_fma_f32 v[202:203], v[192:193], v[96:97], v[202:203]
	ds_read_b128 v[190:193], v57 offset:12960
	v_mad_u32_u24 v61, v55, 47, v51
	ds_read_u16 v59, v61
	ds_read_b32 v204, v53 offset:188
	v_pk_fma_f32 v[246:247], v[194:195], v[34:35], 0 op_sel_hi:[1,1,0]
	v_pk_fma_f32 v[248:249], v[196:197], v[36:37], 0 op_sel_hi:[1,1,0]
	ds_read_b128 v[194:197], v57 offset:13184
	v_add_f32_e32 v250, v250, v251
	v_pk_fma_f32 v[246:247], v[214:215], v[86:87], v[246:247]
	v_pk_fma_f32 v[248:249], v[216:217], v[88:89], v[248:249]
	ds_read_b128 v[214:217], v57 offset:13200
	v_add_f32_e32 v202, v202, v203
	v_pk_fma_f32 v[246:247], v[238:239], v[90:91], v[246:247]
	v_pk_fma_f32 v[248:249], v[240:241], v[92:93], v[248:249]
	ds_read_b128 v[238:241], v57 offset:13216
	v_lshlrev_b32_e32 v221, 16, v221
	v_add_f32_e32 v250, v250, v202
	v_add_f32_e32 v250, v250, v103
	v_fma_f32 v95, v220, v221, -v250
	v_pk_fma_f32 v[246:247], v[242:243], v[94:95], v[246:247]
	v_pk_fma_f32 v[248:249], v[244:245], v[96:97], v[248:249]
	ds_read_b128 v[242:245], v57 offset:13232
	s_waitcnt lgkmcnt(5)
	v_pk_fma_f32 v[250:251], v[198:199], v[34:35], 0 op_sel_hi:[1,1,0]
	v_pk_fma_f32 v[202:203], v[200:201], v[36:37], 0 op_sel_hi:[1,1,0]
	v_mad_u32_u24 v61, v55, 48, v51
	ds_read_u16 v221, v61
	ds_read_b32 v220, v53 offset:192
	ds_read_b128 v[198:201], v57 offset:13456
	v_add_f32_e32 v246, v246, v247
	v_pk_fma_f32 v[250:251], v[206:207], v[86:87], v[250:251]
	v_pk_fma_f32 v[202:203], v[208:209], v[88:89], v[202:203]
	ds_read_b128 v[206:209], v57 offset:13472
	v_add_f32_e32 v248, v248, v249
	v_pk_fma_f32 v[250:251], v[210:211], v[90:91], v[250:251]
	v_pk_fma_f32 v[202:203], v[212:213], v[92:93], v[202:203]
	ds_read_b128 v[210:213], v57 offset:13488
	v_lshlrev_b32_e32 v227, 16, v227
	v_add_f32_e32 v246, v246, v248
	v_add_f32_e32 v246, v246, v104
	v_fma_f32 v96, v226, v227, -v246
	v_pk_fma_f32 v[250:251], v[190:191], v[94:95], v[250:251]
	v_pk_fma_f32 v[202:203], v[192:193], v[96:97], v[202:203]
	ds_read_b128 v[190:193], v57 offset:13504
	s_waitcnt lgkmcnt(5)
	v_pk_fma_f32 v[246:247], v[194:195], v[34:35], 0 op_sel_hi:[1,1,0]
	v_pk_fma_f32 v[248:249], v[196:197], v[36:37], 0 op_sel_hi:[1,1,0]
	ds_read_b128 v[194:197], v57 offset:13520
	v_mad_u32_u24 v61, v55, 49, v51
	ds_read_u16 v227, v61
	ds_read_b32 v226, v53 offset:196
	v_add_f32_e32 v250, v250, v251
	v_pk_fma_f32 v[246:247], v[214:215], v[86:87], v[246:247]
	v_pk_fma_f32 v[248:249], v[216:217], v[88:89], v[248:249]
	ds_read_b128 v[214:217], v57 offset:13728
	v_add_f32_e32 v202, v202, v203
	v_pk_fma_f32 v[246:247], v[238:239], v[90:91], v[246:247]
	v_pk_fma_f32 v[248:249], v[240:241], v[92:93], v[248:249]
	ds_read_b128 v[238:241], v57 offset:13744
	v_lshlrev_b32_e32 v59, 16, v59
	v_add_f32_e32 v250, v250, v202
	v_add_f32_e32 v250, v250, v105
	v_fma_f32 v97, v204, v59, -v250
	v_pk_fma_f32 v[246:247], v[242:243], v[94:95], v[246:247]
	v_pk_fma_f32 v[248:249], v[244:245], v[96:97], v[248:249]
	ds_read_b128 v[242:245], v57 offset:13760
	s_waitcnt lgkmcnt(5)
	v_pk_fma_f32 v[250:251], v[198:199], v[34:35], 0 op_sel_hi:[1,1,0]
	v_pk_fma_f32 v[202:203], v[200:201], v[36:37], 0 op_sel_hi:[1,1,0]
	ds_read_b128 v[198:201], v57 offset:13776
	v_add_f32_e32 v246, v246, v247
	v_pk_fma_f32 v[250:251], v[206:207], v[86:87], v[250:251]
	v_pk_fma_f32 v[202:203], v[208:209], v[88:89], v[202:203]
	ds_read_b128 v[206:209], v57 offset:13792
	v_mad_u32_u24 v61, v55, 50, v51
	ds_read_u16 v59, v61
	ds_read_b32 v204, v53 offset:200
	v_add_f32_e32 v248, v248, v249
	v_pk_fma_f32 v[250:251], v[210:211], v[90:91], v[250:251]
	v_pk_fma_f32 v[202:203], v[212:213], v[92:93], v[202:203]
	ds_read_b128 v[210:213], v57 offset:14000
	v_lshlrev_b32_e32 v221, 16, v221
	v_pk_fma_f32 v[250:251], v[190:191], v[94:95], v[250:251]
	v_pk_fma_f32 v[202:203], v[192:193], v[96:97], v[202:203]
	ds_read_b128 v[190:193], v57 offset:14016
	v_add_f32_e32 v246, v246, v248
	v_add_f32_e32 v246, v246, v182
	v_fma_f32 v98, v220, v221, -v246
	v_pk_fma_f32 v[250:251], v[194:195], v[98:99], v[250:251]
	v_pk_fma_f32 v[202:203], v[196:197], v[100:101], v[202:203]
	ds_read_b128 v[194:197], v57 offset:14032
	s_waitcnt lgkmcnt(5)
	v_pk_fma_f32 v[246:247], v[214:215], v[34:35], 0 op_sel_hi:[1,1,0]
	v_pk_fma_f32 v[248:249], v[216:217], v[36:37], 0 op_sel_hi:[1,1,0]
	ds_read_b128 v[214:217], v57 offset:14048
	v_add_f32_e32 v250, v250, v251
	v_pk_fma_f32 v[246:247], v[238:239], v[86:87], v[246:247]
	v_pk_fma_f32 v[248:249], v[240:241], v[88:89], v[248:249]
	ds_read_b128 v[238:241], v57 offset:14064
	v_mad_u32_u24 v61, v55, 51, v51
	ds_read_u16 v221, v61
	ds_read_b32 v220, v53 offset:204
	v_add_f32_e32 v202, v202, v203
	v_pk_fma_f32 v[246:247], v[242:243], v[90:91], v[246:247]
	v_pk_fma_f32 v[248:249], v[244:245], v[92:93], v[248:249]
	ds_read_b128 v[242:245], v57 offset:14272
	v_lshlrev_b32_e32 v227, 16, v227
	v_pk_fma_f32 v[246:247], v[198:199], v[94:95], v[246:247]
	v_pk_fma_f32 v[248:249], v[200:201], v[96:97], v[248:249]
	ds_read_b128 v[198:201], v57 offset:14288
	v_add_f32_e32 v250, v250, v202
	v_add_f32_e32 v250, v250, v183
	v_fma_f32 v99, v226, v227, -v250
	v_pk_fma_f32 v[246:247], v[206:207], v[98:99], v[246:247]
	v_pk_fma_f32 v[248:249], v[208:209], v[100:101], v[248:249]
	ds_read_b128 v[206:209], v57 offset:14304
	s_waitcnt lgkmcnt(5)
	v_pk_fma_f32 v[250:251], v[210:211], v[34:35], 0 op_sel_hi:[1,1,0]
	v_pk_fma_f32 v[202:203], v[212:213], v[36:37], 0 op_sel_hi:[1,1,0]
	ds_read_b128 v[210:213], v57 offset:14320
	v_add_f32_e32 v246, v246, v247
	v_pk_fma_f32 v[250:251], v[190:191], v[86:87], v[250:251]
	v_pk_fma_f32 v[202:203], v[192:193], v[88:89], v[202:203]
	ds_read_b128 v[190:193], v57 offset:14336
	v_mad_u32_u24 v61, v55, 52, v51
	ds_read_u16 v227, v61
	ds_read_b32 v226, v53 offset:208
	v_add_f32_e32 v248, v248, v249
	v_pk_fma_f32 v[250:251], v[194:195], v[90:91], v[250:251]
	v_pk_fma_f32 v[202:203], v[196:197], v[92:93], v[202:203]
	ds_read_b128 v[194:197], v57 offset:14544
	v_lshlrev_b32_e32 v59, 16, v59
	v_pk_fma_f32 v[250:251], v[214:215], v[94:95], v[250:251]
	v_pk_fma_f32 v[202:203], v[216:217], v[96:97], v[202:203]
	ds_read_b128 v[214:217], v57 offset:14560
	v_add_f32_e32 v246, v246, v248
	v_add_f32_e32 v246, v246, v184
	v_fma_f32 v100, v204, v59, -v246
	v_pk_fma_f32 v[250:251], v[238:239], v[98:99], v[250:251]
	v_pk_fma_f32 v[202:203], v[240:241], v[100:101], v[202:203]
	ds_read_b128 v[238:241], v57 offset:14576
	s_waitcnt lgkmcnt(5)
	v_pk_fma_f32 v[246:247], v[242:243], v[34:35], 0 op_sel_hi:[1,1,0]
	v_pk_fma_f32 v[248:249], v[244:245], v[36:37], 0 op_sel_hi:[1,1,0]
	ds_read_b128 v[242:245], v57 offset:14592
	v_add_f32_e32 v250, v250, v251
	v_pk_fma_f32 v[246:247], v[198:199], v[86:87], v[246:247]
	v_pk_fma_f32 v[248:249], v[200:201], v[88:89], v[248:249]
	ds_read_b128 v[198:201], v57 offset:14608
	v_add_f32_e32 v202, v202, v203
	v_pk_fma_f32 v[246:247], v[206:207], v[90:91], v[246:247]
	v_pk_fma_f32 v[248:249], v[208:209], v[92:93], v[248:249]
	ds_read_b128 v[206:209], v57 offset:14624
	v_mad_u32_u24 v61, v55, 53, v51
	ds_read_u16 v59, v61
	ds_read_b32 v204, v53 offset:212
	v_lshlrev_b32_e32 v221, 16, v221
	v_pk_fma_f32 v[246:247], v[210:211], v[94:95], v[246:247]
	v_pk_fma_f32 v[248:249], v[212:213], v[96:97], v[248:249]
	ds_read_b128 v[210:213], v57 offset:14816
	v_add_f32_e32 v250, v250, v202
	v_add_f32_e32 v250, v250, v185
	v_fma_f32 v101, v220, v221, -v250
	v_pk_fma_f32 v[246:247], v[190:191], v[98:99], v[246:247]
	v_pk_fma_f32 v[248:249], v[192:193], v[100:101], v[248:249]
	ds_read_b128 v[190:193], v57 offset:14832
	s_waitcnt lgkmcnt(5)
	v_pk_fma_f32 v[250:251], v[194:195], v[34:35], 0 op_sel_hi:[1,1,0]
	v_pk_fma_f32 v[202:203], v[196:197], v[36:37], 0 op_sel_hi:[1,1,0]
	ds_read_b128 v[194:197], v57 offset:14848
	v_add_f32_e32 v246, v246, v247
	v_pk_fma_f32 v[250:251], v[214:215], v[86:87], v[250:251]
	v_pk_fma_f32 v[202:203], v[216:217], v[88:89], v[202:203]
	ds_read_b128 v[214:217], v57 offset:14864
	v_add_f32_e32 v248, v248, v249
	v_pk_fma_f32 v[250:251], v[238:239], v[90:91], v[250:251]
	v_pk_fma_f32 v[202:203], v[240:241], v[92:93], v[202:203]
	ds_read_b128 v[238:241], v57 offset:14880
	v_lshlrev_b32_e32 v227, 16, v227
	v_pk_fma_f32 v[250:251], v[242:243], v[94:95], v[250:251]
	v_pk_fma_f32 v[202:203], v[244:245], v[96:97], v[202:203]
	ds_read_b128 v[242:245], v57 offset:14896
	v_mad_u32_u24 v61, v55, 54, v51
	ds_read_u16 v221, v61
	ds_read_b32 v220, v53 offset:216
	v_add_f32_e32 v246, v246, v248
	v_pk_fma_f32 v[250:251], v[198:199], v[98:99], v[250:251]
	v_pk_fma_f32 v[202:203], v[200:201], v[100:101], v[202:203]
	ds_read_b128 v[198:201], v57 offset:15088
	v_add_f32_e32 v246, v246, v106
	v_fma_f32 v102, v226, v227, -v246
	s_waitcnt lgkmcnt(5)
	v_pk_fma_f32 v[250:251], v[206:207], v[102:103], v[250:251]
	v_pk_fma_f32 v[202:203], v[208:209], v[104:105], v[202:203]
	ds_read_b128 v[206:209], v57 offset:15104
	v_pk_fma_f32 v[246:247], v[210:211], v[34:35], 0 op_sel_hi:[1,1,0]
	v_pk_fma_f32 v[248:249], v[212:213], v[36:37], 0 op_sel_hi:[1,1,0]
	ds_read_b128 v[210:213], v57 offset:15120
	v_add_f32_e32 v250, v250, v251
	v_pk_fma_f32 v[246:247], v[190:191], v[86:87], v[246:247]
	v_pk_fma_f32 v[248:249], v[192:193], v[88:89], v[248:249]
	ds_read_b128 v[190:193], v57 offset:15136
	v_add_f32_e32 v202, v202, v203
	v_pk_fma_f32 v[246:247], v[194:195], v[90:91], v[246:247]
	v_pk_fma_f32 v[248:249], v[196:197], v[92:93], v[248:249]
	ds_read_b128 v[194:197], v57 offset:15152
	v_lshlrev_b32_e32 v59, 16, v59
	v_pk_fma_f32 v[246:247], v[214:215], v[94:95], v[246:247]
	v_pk_fma_f32 v[248:249], v[216:217], v[96:97], v[248:249]
	ds_read_b128 v[214:217], v57 offset:15168
	v_mad_u32_u24 v61, v55, 55, v51
	ds_read_u16 v227, v61
	ds_read_b32 v226, v53 offset:220
	v_add_f32_e32 v250, v250, v202
	s_waitcnt lgkmcnt(5)
	v_pk_fma_f32 v[246:247], v[238:239], v[98:99], v[246:247]
	v_pk_fma_f32 v[248:249], v[240:241], v[100:101], v[248:249]
	ds_read_b128 v[238:241], v57 offset:15360
	v_add_f32_e32 v250, v250, v107
	v_fma_f32 v103, v204, v59, -v250
	v_pk_fma_f32 v[246:247], v[242:243], v[102:103], v[246:247]
	v_pk_fma_f32 v[248:249], v[244:245], v[104:105], v[248:249]
	ds_read_b128 v[242:245], v57 offset:15376
	v_pk_fma_f32 v[250:251], v[198:199], v[34:35], 0 op_sel_hi:[1,1,0]
	v_pk_fma_f32 v[202:203], v[200:201], v[36:37], 0 op_sel_hi:[1,1,0]
	ds_read_b128 v[198:201], v57 offset:15392
	v_add_f32_e32 v246, v246, v247
	v_pk_fma_f32 v[250:251], v[206:207], v[86:87], v[250:251]
	v_pk_fma_f32 v[202:203], v[208:209], v[88:89], v[202:203]
	ds_read_b128 v[206:209], v57 offset:15408
	v_add_f32_e32 v248, v248, v249
	v_pk_fma_f32 v[250:251], v[210:211], v[90:91], v[250:251]
	v_pk_fma_f32 v[202:203], v[212:213], v[92:93], v[202:203]
	ds_read_b128 v[210:213], v57 offset:15424
	v_lshlrev_b32_e32 v221, 16, v221
	s_waitcnt lgkmcnt(5)
	v_pk_fma_f32 v[250:251], v[190:191], v[94:95], v[250:251]
	v_pk_fma_f32 v[202:203], v[192:193], v[96:97], v[202:203]
	ds_read_b128 v[190:193], v57 offset:15440
	v_mad_u32_u24 v61, v55, 56, v51
	ds_read_u16 v59, v61
	ds_read_b32 v204, v53 offset:224
	v_add_f32_e32 v246, v246, v248
	v_pk_fma_f32 v[250:251], v[194:195], v[98:99], v[250:251]
	v_pk_fma_f32 v[202:203], v[196:197], v[100:101], v[202:203]
	ds_read_b128 v[194:197], v57 offset:15632
	v_add_f32_e32 v246, v246, v108
	v_fma_f32 v104, v220, v221, -v246
	v_pk_fma_f32 v[250:251], v[214:215], v[102:103], v[250:251]
	v_pk_fma_f32 v[202:203], v[216:217], v[104:105], v[202:203]
	ds_read_b128 v[214:217], v57 offset:15648
	s_waitcnt lgkmcnt(5)
	v_pk_fma_f32 v[246:247], v[238:239], v[34:35], 0 op_sel_hi:[1,1,0]
	v_pk_fma_f32 v[248:249], v[240:241], v[36:37], 0 op_sel_hi:[1,1,0]
	ds_read_b128 v[238:241], v57 offset:15664
	v_add_f32_e32 v250, v250, v251
	v_pk_fma_f32 v[246:247], v[242:243], v[86:87], v[246:247]
	v_pk_fma_f32 v[248:249], v[244:245], v[88:89], v[248:249]
	ds_read_b128 v[242:245], v57 offset:15680
	v_add_f32_e32 v202, v202, v203
	v_pk_fma_f32 v[246:247], v[198:199], v[90:91], v[246:247]
	v_pk_fma_f32 v[248:249], v[200:201], v[92:93], v[248:249]
	ds_read_b128 v[198:201], v57 offset:15696
	v_lshlrev_b32_e32 v227, 16, v227
	v_pk_fma_f32 v[246:247], v[206:207], v[94:95], v[246:247]
	v_pk_fma_f32 v[248:249], v[208:209], v[96:97], v[248:249]
	ds_read_b128 v[206:209], v57 offset:15712
	v_add_f32_e32 v250, v250, v202
	v_pk_fma_f32 v[246:247], v[210:211], v[98:99], v[246:247]
	v_pk_fma_f32 v[248:249], v[212:213], v[100:101], v[248:249]
	ds_read_b128 v[210:213], v57 offset:15728
	v_mad_u32_u24 v61, v55, 57, v51
	ds_read_u16 v221, v61
	ds_read_b32 v220, v53 offset:228
	v_add_f32_e32 v250, v250, v109
	v_fma_f32 v105, v226, v227, -v250
	s_waitcnt lgkmcnt(5)
	v_pk_fma_f32 v[246:247], v[190:191], v[102:103], v[246:247]
	v_pk_fma_f32 v[248:249], v[192:193], v[104:105], v[248:249]
	ds_read_b128 v[190:193], v57 offset:15904
	v_pk_fma_f32 v[250:251], v[194:195], v[34:35], 0 op_sel_hi:[1,1,0]
	v_pk_fma_f32 v[202:203], v[196:197], v[36:37], 0 op_sel_hi:[1,1,0]
	ds_read_b128 v[194:197], v57 offset:15920
	v_add_f32_e32 v246, v246, v247
	v_pk_fma_f32 v[250:251], v[214:215], v[86:87], v[250:251]
	v_pk_fma_f32 v[202:203], v[216:217], v[88:89], v[202:203]
	ds_read_b128 v[214:217], v57 offset:15936
	v_add_f32_e32 v248, v248, v249
	v_pk_fma_f32 v[250:251], v[238:239], v[90:91], v[250:251]
	v_pk_fma_f32 v[202:203], v[240:241], v[92:93], v[202:203]
	ds_read_b128 v[238:241], v57 offset:15952
	v_lshlrev_b32_e32 v59, 16, v59
	v_pk_fma_f32 v[250:251], v[242:243], v[94:95], v[250:251]
	v_pk_fma_f32 v[202:203], v[244:245], v[96:97], v[202:203]
	ds_read_b128 v[242:245], v57 offset:15968
	v_add_f32_e32 v246, v246, v248
	s_waitcnt lgkmcnt(5)
	v_pk_fma_f32 v[250:251], v[198:199], v[98:99], v[250:251]
	v_pk_fma_f32 v[202:203], v[200:201], v[100:101], v[202:203]
	ds_read_b128 v[198:201], v57 offset:15984
	v_add_f32_e32 v246, v246, v186
	v_pk_fma_f32 v[250:251], v[206:207], v[102:103], v[250:251]
	v_pk_fma_f32 v[202:203], v[208:209], v[104:105], v[202:203]
	ds_read_b128 v[206:209], v57 offset:16000
	v_mad_u32_u24 v61, v55, 58, v51
	ds_read_u16 v227, v61
	ds_read_b32 v226, v53 offset:232
	v_fma_f32 v106, v204, v59, -v246
	v_pk_fma_f32 v[250:251], v[210:211], v[106:107], v[250:251]
	v_pk_fma_f32 v[202:203], v[212:213], v[108:109], v[202:203]
	ds_read_b128 v[210:213], v57 offset:16176
	s_waitcnt lgkmcnt(5)
	v_pk_fma_f32 v[246:247], v[190:191], v[34:35], 0 op_sel_hi:[1,1,0]
	v_pk_fma_f32 v[248:249], v[192:193], v[36:37], 0 op_sel_hi:[1,1,0]
	ds_read_b128 v[190:193], v57 offset:16192
	v_add_f32_e32 v250, v250, v251
	v_pk_fma_f32 v[246:247], v[194:195], v[86:87], v[246:247]
	v_pk_fma_f32 v[248:249], v[196:197], v[88:89], v[248:249]
	ds_read_b128 v[194:197], v57 offset:16208
	v_add_f32_e32 v202, v202, v203
	v_pk_fma_f32 v[246:247], v[214:215], v[90:91], v[246:247]
	v_pk_fma_f32 v[248:249], v[216:217], v[92:93], v[248:249]
	ds_read_b128 v[214:217], v57 offset:16224
	v_lshlrev_b32_e32 v221, 16, v221
	v_pk_fma_f32 v[246:247], v[238:239], v[94:95], v[246:247]
	v_pk_fma_f32 v[248:249], v[240:241], v[96:97], v[248:249]
	ds_read_b128 v[238:241], v57 offset:16240
	v_add_f32_e32 v250, v250, v202
	v_pk_fma_f32 v[246:247], v[242:243], v[98:99], v[246:247]
	v_pk_fma_f32 v[248:249], v[244:245], v[100:101], v[248:249]
	ds_read_b128 v[242:245], v57 offset:16256
	v_add_f32_e32 v250, v250, v187
	s_waitcnt lgkmcnt(5)
	v_pk_fma_f32 v[246:247], v[198:199], v[102:103], v[246:247]
	v_pk_fma_f32 v[248:249], v[200:201], v[104:105], v[248:249]
	ds_read_b128 v[198:201], v57 offset:16272
	v_mad_u32_u24 v61, v55, 59, v51
	ds_read_u16 v59, v61
	ds_read_b32 v204, v53 offset:236
	v_fma_f32 v107, v220, v221, -v250
	v_pk_fma_f32 v[246:247], v[206:207], v[106:107], v[246:247]
	v_pk_fma_f32 v[248:249], v[208:209], v[108:109], v[248:249]
	ds_read_b128 v[206:209], v57 offset:16448
	v_pk_fma_f32 v[250:251], v[210:211], v[34:35], 0 op_sel_hi:[1,1,0]
	v_pk_fma_f32 v[202:203], v[212:213], v[36:37], 0 op_sel_hi:[1,1,0]
	ds_read_b128 v[210:213], v57 offset:16464
	v_add_f32_e32 v246, v246, v247
	s_waitcnt lgkmcnt(5)
	v_pk_fma_f32 v[250:251], v[190:191], v[86:87], v[250:251]
	v_pk_fma_f32 v[202:203], v[192:193], v[88:89], v[202:203]
	ds_read_b128 v[190:193], v57 offset:16480
	v_add_f32_e32 v248, v248, v249
	v_pk_fma_f32 v[250:251], v[194:195], v[90:91], v[250:251]
	v_pk_fma_f32 v[202:203], v[196:197], v[92:93], v[202:203]
	ds_read_b128 v[194:197], v57 offset:16496
	v_lshlrev_b32_e32 v227, 16, v227
	v_pk_fma_f32 v[250:251], v[214:215], v[94:95], v[250:251]
	v_pk_fma_f32 v[202:203], v[216:217], v[96:97], v[202:203]
	ds_read_b128 v[214:217], v57 offset:16512
	v_add_f32_e32 v246, v246, v248
	v_pk_fma_f32 v[250:251], v[238:239], v[98:99], v[250:251]
	v_pk_fma_f32 v[202:203], v[240:241], v[100:101], v[202:203]
	ds_read_b128 v[238:241], v57 offset:16528
	v_add_f32_e32 v246, v246, v188
	v_pk_fma_f32 v[250:251], v[242:243], v[102:103], v[250:251]
	v_pk_fma_f32 v[202:203], v[244:245], v[104:105], v[202:203]
	ds_read_b128 v[242:245], v57 offset:16544
	v_mad_u32_u24 v61, v55, 60, v51
	ds_read_u16 v221, v61
	ds_read_b32 v220, v53 offset:240
	v_fma_f32 v108, v226, v227, -v246
	s_waitcnt lgkmcnt(5)
	v_pk_fma_f32 v[250:251], v[198:199], v[106:107], v[250:251]
	v_pk_fma_f32 v[202:203], v[200:201], v[108:109], v[202:203]
	ds_read_b128 v[198:201], v57 offset:16720
	v_pk_fma_f32 v[246:247], v[206:207], v[34:35], 0 op_sel_hi:[1,1,0]
	v_pk_fma_f32 v[248:249], v[208:209], v[36:37], 0 op_sel_hi:[1,1,0]
	ds_read_b128 v[206:209], v57 offset:16736
	v_add_f32_e32 v250, v250, v251
	v_pk_fma_f32 v[246:247], v[210:211], v[86:87], v[246:247]
	v_pk_fma_f32 v[248:249], v[212:213], v[88:89], v[248:249]
	ds_read_b128 v[210:213], v57 offset:16752
	v_add_f32_e32 v202, v202, v203
	v_pk_fma_f32 v[246:247], v[190:191], v[90:91], v[246:247]
	v_pk_fma_f32 v[248:249], v[192:193], v[92:93], v[248:249]
	ds_read_b128 v[190:193], v57 offset:16768
	v_lshlrev_b32_e32 v59, 16, v59
	v_pk_fma_f32 v[246:247], v[194:195], v[94:95], v[246:247]
	v_pk_fma_f32 v[248:249], v[196:197], v[96:97], v[248:249]
	ds_read_b128 v[194:197], v57 offset:16784
	v_add_f32_e32 v250, v250, v202
	s_waitcnt lgkmcnt(5)
	v_pk_fma_f32 v[246:247], v[214:215], v[98:99], v[246:247]
	v_pk_fma_f32 v[248:249], v[216:217], v[100:101], v[248:249]
	ds_read_b128 v[214:217], v57 offset:16800
	v_add_f32_e32 v250, v250, v189
	v_pk_fma_f32 v[246:247], v[238:239], v[102:103], v[246:247]
	v_pk_fma_f32 v[248:249], v[240:241], v[104:105], v[248:249]
	ds_read_b128 v[238:241], v57 offset:16816
	v_fma_f32 v109, v204, v59, -v250
	v_pk_fma_f32 v[246:247], v[242:243], v[106:107], v[246:247]
	v_pk_fma_f32 v[248:249], v[244:245], v[108:109], v[248:249]
	ds_read_b128 v[242:245], v57 offset:16832
	v_mad_u32_u24 v61, v55, 61, v51
	ds_read_u16 v227, v61
	ds_read_b32 v226, v53 offset:244
	s_waitcnt lgkmcnt(5)
	v_pk_fma_f32 v[250:251], v[198:199], v[34:35], 0 op_sel_hi:[1,1,0]
	v_pk_fma_f32 v[202:203], v[200:201], v[36:37], 0 op_sel_hi:[1,1,0]
	ds_read_b128 v[198:201], v57 offset:16992
	v_add_f32_e32 v246, v246, v247
	v_pk_fma_f32 v[250:251], v[206:207], v[86:87], v[250:251]
	v_pk_fma_f32 v[202:203], v[208:209], v[88:89], v[202:203]
	ds_read_b128 v[206:209], v57 offset:17008
	v_add_f32_e32 v248, v248, v249
	v_pk_fma_f32 v[250:251], v[210:211], v[90:91], v[250:251]
	v_pk_fma_f32 v[202:203], v[212:213], v[92:93], v[202:203]
	ds_read_b128 v[210:213], v57 offset:17024
	v_lshlrev_b32_e32 v221, 16, v221
	v_pk_fma_f32 v[250:251], v[190:191], v[94:95], v[250:251]
	v_pk_fma_f32 v[202:203], v[192:193], v[96:97], v[202:203]
	ds_read_b128 v[190:193], v57 offset:17040
	v_add_f32_e32 v246, v246, v248
	v_pk_fma_f32 v[250:251], v[194:195], v[98:99], v[250:251]
	v_pk_fma_f32 v[202:203], v[196:197], v[100:101], v[202:203]
	ds_read_b128 v[194:197], v57 offset:17056
	v_add_f32_e32 v246, v246, v110
	s_waitcnt lgkmcnt(5)
	v_pk_fma_f32 v[250:251], v[214:215], v[102:103], v[250:251]
	v_pk_fma_f32 v[202:203], v[216:217], v[104:105], v[202:203]
	ds_read_b128 v[214:217], v57 offset:17072
	v_fma_f32 v110, v220, v221, -v246
	v_pk_fma_f32 v[250:251], v[238:239], v[106:107], v[250:251]
	v_pk_fma_f32 v[202:203], v[240:241], v[108:109], v[202:203]
	ds_read_b128 v[238:241], v57 offset:17088
	v_pk_fma_f32 v[250:251], v[242:243], v[110:111], v[250:251]
	v_pk_fma_f32 v[202:203], v[244:245], v[112:113], v[202:203]
	ds_read_b128 v[242:245], v57 offset:17104
	v_mad_u32_u24 v61, v55, 62, v51
	ds_read_u16 v59, v61
	ds_read_b32 v204, v53 offset:248
	s_waitcnt lgkmcnt(5)
	v_pk_fma_f32 v[246:247], v[198:199], v[34:35], 0 op_sel_hi:[1,1,0]
	v_pk_fma_f32 v[248:249], v[200:201], v[36:37], 0 op_sel_hi:[1,1,0]
	ds_read_b128 v[198:201], v57 offset:17264
	v_add_f32_e32 v250, v250, v251
	v_pk_fma_f32 v[246:247], v[206:207], v[86:87], v[246:247]
	v_pk_fma_f32 v[248:249], v[208:209], v[88:89], v[248:249]
	ds_read_b128 v[206:209], v57 offset:17280
	v_add_f32_e32 v202, v202, v203
	v_pk_fma_f32 v[246:247], v[210:211], v[90:91], v[246:247]
	v_pk_fma_f32 v[248:249], v[212:213], v[92:93], v[248:249]
	ds_read_b128 v[210:213], v57 offset:17296
	v_lshlrev_b32_e32 v227, 16, v227
	v_pk_fma_f32 v[246:247], v[190:191], v[94:95], v[246:247]
	v_pk_fma_f32 v[248:249], v[192:193], v[96:97], v[248:249]
	ds_read_b128 v[190:193], v57 offset:17312
	v_add_f32_e32 v250, v250, v202
	v_pk_fma_f32 v[246:247], v[194:195], v[98:99], v[246:247]
	v_pk_fma_f32 v[248:249], v[196:197], v[100:101], v[248:249]
	ds_read_b128 v[194:197], v57 offset:17328
	v_add_f32_e32 v250, v250, v111
	s_waitcnt lgkmcnt(5)
	v_pk_fma_f32 v[246:247], v[214:215], v[102:103], v[246:247]
	v_pk_fma_f32 v[248:249], v[216:217], v[104:105], v[248:249]
	ds_read_b128 v[214:217], v57 offset:17344
	v_fma_f32 v111, v226, v227, -v250
	v_pk_fma_f32 v[246:247], v[238:239], v[106:107], v[246:247]
	v_pk_fma_f32 v[248:249], v[240:241], v[108:109], v[248:249]
	ds_read_b128 v[238:241], v57 offset:17360
	v_pk_fma_f32 v[246:247], v[242:243], v[110:111], v[246:247]
	v_pk_fma_f32 v[248:249], v[244:245], v[112:113], v[248:249]
	ds_read_b128 v[242:245], v57 offset:17376
	v_mad_u32_u24 v61, v55, 63, v51
	ds_read_u16 v221, v61
	ds_read_b32 v220, v53 offset:252
	s_waitcnt lgkmcnt(5)
	v_pk_fma_f32 v[250:251], v[198:199], v[34:35], 0 op_sel_hi:[1,1,0]
	v_pk_fma_f32 v[202:203], v[200:201], v[36:37], 0 op_sel_hi:[1,1,0]
	v_add_f32_e32 v246, v246, v247
	v_pk_fma_f32 v[250:251], v[206:207], v[86:87], v[250:251]
	v_pk_fma_f32 v[202:203], v[208:209], v[88:89], v[202:203]
	v_add_f32_e32 v248, v248, v249
	v_pk_fma_f32 v[250:251], v[210:211], v[90:91], v[250:251]
	v_pk_fma_f32 v[202:203], v[212:213], v[92:93], v[202:203]
	v_lshlrev_b32_e32 v59, 16, v59
	v_pk_fma_f32 v[250:251], v[190:191], v[94:95], v[250:251]
	v_pk_fma_f32 v[202:203], v[192:193], v[96:97], v[202:203]
	v_add_f32_e32 v246, v246, v248
	v_pk_fma_f32 v[250:251], v[194:195], v[98:99], v[250:251]
	v_pk_fma_f32 v[202:203], v[196:197], v[100:101], v[202:203]
	v_add_f32_e32 v246, v246, v112
	s_waitcnt lgkmcnt(4)
	v_pk_fma_f32 v[250:251], v[214:215], v[102:103], v[250:251]
	v_pk_fma_f32 v[202:203], v[216:217], v[104:105], v[202:203]
	v_fma_f32 v112, v204, v59, -v246
	s_waitcnt lgkmcnt(3)
	v_pk_fma_f32 v[250:251], v[238:239], v[106:107], v[250:251]
	v_pk_fma_f32 v[202:203], v[240:241], v[108:109], v[202:203]
	s_waitcnt lgkmcnt(2)
	v_pk_fma_f32 v[250:251], v[242:243], v[110:111], v[250:251]
	v_pk_fma_f32 v[202:203], v[244:245], v[112:113], v[202:203]
	v_add_f32_e32 v250, v250, v251
	v_add_f32_e32 v202, v202, v203
	s_waitcnt lgkmcnt(0)
	v_lshlrev_b32_e32 v221, 16, v221
	v_add_f32_e32 v250, v250, v202
	v_add_f32_e32 v250, v250, v113
	v_fma_f32 v2, v220, v221, -v250
	s_setprio 0
	s_and_saveexec_b64 s[0:1], vcc
	s_xor_b64 s[0:1], exec, s[0:1]
	s_cbranch_execz .LBB0_194
	v_lshl_add_u32 v47, v47, 1, 0
	v_bfe_u32 v49, v0, 16, 1
	v_add_u32_e32 v47, 0x1d900, v47
	v_add3_u32 v0, v0, v49, s33
	ds_write_b16_d16_hi v47, v0
	v_bfe_u32 v0, v3, 16, 1
	v_add3_u32 v0, v3, v0, s33
	ds_write_b16_d16_hi v47, v0 offset:256
	v_bfe_u32 v0, v4, 16, 1
	v_add3_u32 v0, v4, v0, s33
	ds_write_b16_d16_hi v47, v0 offset:512
	v_bfe_u32 v0, v5, 16, 1
	v_add3_u32 v0, v5, v0, s33
	ds_write_b16_d16_hi v47, v0 offset:768
	v_bfe_u32 v0, v6, 16, 1
	v_add3_u32 v0, v6, v0, s33
	ds_write_b16_d16_hi v47, v0 offset:1024
	v_bfe_u32 v0, v7, 16, 1
	v_add3_u32 v0, v7, v0, s33
	ds_write_b16_d16_hi v47, v0 offset:1280
	v_bfe_u32 v0, v8, 16, 1
	v_add3_u32 v0, v8, v0, s33
	ds_write_b16_d16_hi v47, v0 offset:1536
	v_bfe_u32 v0, v9, 16, 1
	v_add3_u32 v0, v9, v0, s33
	ds_write_b16_d16_hi v47, v0 offset:1792
	v_bfe_u32 v0, v10, 16, 1
	v_add3_u32 v0, v10, v0, s33
	ds_write_b16_d16_hi v47, v0 offset:2048
	v_bfe_u32 v0, v11, 16, 1
	v_add3_u32 v0, v11, v0, s33
	ds_write_b16_d16_hi v47, v0 offset:2304
	v_bfe_u32 v0, v12, 16, 1
	v_add3_u32 v0, v12, v0, s33
	ds_write_b16_d16_hi v47, v0 offset:2560
	v_bfe_u32 v0, v13, 16, 1
	v_add3_u32 v0, v13, v0, s33
	ds_write_b16_d16_hi v47, v0 offset:2816
	v_bfe_u32 v0, v14, 16, 1
	v_add3_u32 v0, v14, v0, s33
	ds_write_b16_d16_hi v47, v0 offset:3072
	v_bfe_u32 v0, v15, 16, 1
	v_add3_u32 v0, v15, v0, s33
	ds_write_b16_d16_hi v47, v0 offset:3328
	v_bfe_u32 v0, v16, 16, 1
	v_add3_u32 v0, v16, v0, s33
	ds_write_b16_d16_hi v47, v0 offset:3584
	v_bfe_u32 v0, v17, 16, 1
	v_add3_u32 v0, v17, v0, s33
	ds_write_b16_d16_hi v47, v0 offset:3840
	v_bfe_u32 v0, v18, 16, 1
	v_add3_u32 v0, v18, v0, s33
	ds_write_b16_d16_hi v47, v0 offset:4096
	v_bfe_u32 v0, v19, 16, 1
	v_add3_u32 v0, v19, v0, s33
	ds_write_b16_d16_hi v47, v0 offset:4352
	v_bfe_u32 v0, v20, 16, 1
	v_add3_u32 v0, v20, v0, s33
	ds_write_b16_d16_hi v47, v0 offset:4608
	v_bfe_u32 v0, v21, 16, 1
	v_add3_u32 v0, v21, v0, s33
	ds_write_b16_d16_hi v47, v0 offset:4864
	v_bfe_u32 v0, v22, 16, 1
	v_add3_u32 v0, v22, v0, s33
	ds_write_b16_d16_hi v47, v0 offset:5120
	v_bfe_u32 v0, v23, 16, 1
	v_add3_u32 v0, v23, v0, s33
	ds_write_b16_d16_hi v47, v0 offset:5376
	v_bfe_u32 v0, v24, 16, 1
	v_add3_u32 v0, v24, v0, s33
	ds_write_b16_d16_hi v47, v0 offset:5632
	v_bfe_u32 v0, v25, 16, 1
	v_add3_u32 v0, v25, v0, s33
	ds_write_b16_d16_hi v47, v0 offset:5888
	v_bfe_u32 v0, v26, 16, 1
	v_add3_u32 v0, v26, v0, s33
	ds_write_b16_d16_hi v47, v0 offset:6144
	v_bfe_u32 v0, v27, 16, 1
	v_add3_u32 v0, v27, v0, s33
	ds_write_b16_d16_hi v47, v0 offset:6400
	v_bfe_u32 v0, v28, 16, 1
	v_add3_u32 v0, v28, v0, s33
	ds_write_b16_d16_hi v47, v0 offset:6656
	v_bfe_u32 v0, v29, 16, 1
	v_add3_u32 v0, v29, v0, s33
	ds_write_b16_d16_hi v47, v0 offset:6912
	v_bfe_u32 v0, v30, 16, 1
	v_add3_u32 v0, v30, v0, s33
	ds_write_b16_d16_hi v47, v0 offset:7168
	v_bfe_u32 v0, v31, 16, 1
	v_add3_u32 v0, v31, v0, s33
	ds_write_b16_d16_hi v47, v0 offset:7424
	v_bfe_u32 v0, v32, 16, 1
	v_add3_u32 v0, v32, v0, s33
	ds_write_b16_d16_hi v47, v0 offset:7680
	v_bfe_u32 v0, v33, 16, 1
	v_add3_u32 v0, v33, v0, s33
	ds_write_b16_d16_hi v47, v0 offset:7936
	v_bfe_u32 v0, v34, 16, 1
	v_add3_u32 v0, v34, v0, s33
	ds_write_b16_d16_hi v47, v0 offset:8192
	v_bfe_u32 v0, v35, 16, 1
	v_add3_u32 v0, v35, v0, s33
	ds_write_b16_d16_hi v47, v0 offset:8448
	v_bfe_u32 v0, v36, 16, 1
	v_add3_u32 v0, v36, v0, s33
	ds_write_b16_d16_hi v47, v0 offset:8704
	v_bfe_u32 v0, v37, 16, 1
	v_add3_u32 v0, v37, v0, s33
	ds_write_b16_d16_hi v47, v0 offset:8960
	v_bfe_u32 v0, v86, 16, 1
	v_add3_u32 v0, v86, v0, s33
	ds_write_b16_d16_hi v47, v0 offset:9216
	v_bfe_u32 v0, v87, 16, 1
	v_add3_u32 v0, v87, v0, s33
	ds_write_b16_d16_hi v47, v0 offset:9472
	v_bfe_u32 v0, v88, 16, 1
	v_add3_u32 v0, v88, v0, s33
	ds_write_b16_d16_hi v47, v0 offset:9728
	v_bfe_u32 v0, v89, 16, 1
	v_add3_u32 v0, v89, v0, s33
	ds_write_b16_d16_hi v47, v0 offset:9984
	v_bfe_u32 v0, v90, 16, 1
	v_add3_u32 v0, v90, v0, s33
	ds_write_b16_d16_hi v47, v0 offset:10240
	v_bfe_u32 v0, v91, 16, 1
	v_add3_u32 v0, v91, v0, s33
	ds_write_b16_d16_hi v47, v0 offset:10496
	v_bfe_u32 v0, v92, 16, 1
	v_add3_u32 v0, v92, v0, s33
	ds_write_b16_d16_hi v47, v0 offset:10752
	v_bfe_u32 v0, v93, 16, 1
	v_add3_u32 v0, v93, v0, s33
	ds_write_b16_d16_hi v47, v0 offset:11008
	v_bfe_u32 v0, v94, 16, 1
	v_add3_u32 v0, v94, v0, s33
	ds_write_b16_d16_hi v47, v0 offset:11264
	v_bfe_u32 v0, v95, 16, 1
	v_add3_u32 v0, v95, v0, s33
	ds_write_b16_d16_hi v47, v0 offset:11520
	v_bfe_u32 v0, v96, 16, 1
	v_add3_u32 v0, v96, v0, s33
	ds_write_b16_d16_hi v47, v0 offset:11776
	v_bfe_u32 v0, v97, 16, 1
	v_add3_u32 v0, v97, v0, s33
	ds_write_b16_d16_hi v47, v0 offset:12032
	v_bfe_u32 v0, v98, 16, 1
	v_add3_u32 v0, v98, v0, s33
	ds_write_b16_d16_hi v47, v0 offset:12288
	v_bfe_u32 v0, v99, 16, 1
	v_add3_u32 v0, v99, v0, s33
	ds_write_b16_d16_hi v47, v0 offset:12544
	v_bfe_u32 v0, v100, 16, 1
	v_add3_u32 v0, v100, v0, s33
	ds_write_b16_d16_hi v47, v0 offset:12800
	v_bfe_u32 v0, v101, 16, 1
	v_add3_u32 v0, v101, v0, s33
	ds_write_b16_d16_hi v47, v0 offset:13056
	v_bfe_u32 v0, v102, 16, 1
	v_add3_u32 v0, v102, v0, s33
	ds_write_b16_d16_hi v47, v0 offset:13312
	v_bfe_u32 v0, v103, 16, 1
	v_add3_u32 v0, v103, v0, s33
	ds_write_b16_d16_hi v47, v0 offset:13568
	v_bfe_u32 v0, v104, 16, 1
	v_add3_u32 v0, v104, v0, s33
	ds_write_b16_d16_hi v47, v0 offset:13824
	v_bfe_u32 v0, v105, 16, 1
	v_add3_u32 v0, v105, v0, s33
	ds_write_b16_d16_hi v47, v0 offset:14080
	v_bfe_u32 v0, v106, 16, 1
	v_add3_u32 v0, v106, v0, s33
	ds_write_b16_d16_hi v47, v0 offset:14336
	v_bfe_u32 v0, v107, 16, 1
	v_add3_u32 v0, v107, v0, s33
	ds_write_b16_d16_hi v47, v0 offset:14592
	v_bfe_u32 v0, v108, 16, 1
	v_add3_u32 v0, v108, v0, s33
	ds_write_b16_d16_hi v47, v0 offset:14848
	v_bfe_u32 v0, v109, 16, 1
	v_add3_u32 v0, v109, v0, s33
	ds_write_b16_d16_hi v47, v0 offset:15104
	v_bfe_u32 v0, v110, 16, 1
	v_add3_u32 v0, v110, v0, s33
	ds_write_b16_d16_hi v47, v0 offset:15360
	v_bfe_u32 v0, v111, 16, 1
	v_add3_u32 v0, v111, v0, s33
	ds_write_b16_d16_hi v47, v0 offset:15616
	v_bfe_u32 v0, v112, 16, 1
	v_add3_u32 v0, v112, v0, s33
	ds_write_b16_d16_hi v47, v0 offset:15872
	v_bfe_u32 v0, v2, 16, 1
	v_add3_u32 v0, v2, v0, s33
	ds_write_b16_d16_hi v47, v0 offset:16128
